# drop NaN-canonicalizing self-max ops in attention softmax max trees (forward sources into max/max3)
# baseline (speedup 1.0000x reference)
; #define LDS_FENCE() asm volatile("s_waitcnt lgkmcnt(0)" ::: "memory")
; __device__ __forceinline__ AttnLd attn_load(const bf16_t* __restrict__ ka, const bf16_t* __restrict__ va, int S, int r, int n0, int lane, int f) {
;     int dsh, cb; attn_geom(f, r, n0, dsh, cb);
;     const int qi = lane & 15, g = lane >> 4, rd = r & ((1 << dsh) - 1), ncls = S >> dsh;
;     const int cA = cb + 8 * (qi >> 2) + (qi & 3), cB = cA + 4;
;     const int cAc = min(max(cA, 0), ncls - 1), cBc = min(max(cB, 0), ncls - 1);
;     const bf16_t* kA = ka + (size_t)(rd + (cAc << dsh)) * 64 + 8 * g;
;     const bf16_t* kB = ka + (size_t)(rd + (cBc << dsh)) * 64 + 8 * g;
;     AttnLd L;
;     L.ka0 = *(const bf16x8*)kA; L.ka1 = *(const bf16x8*)(kA + 32); L.kb0 = *(const bf16x8*)kB; L.kb1 = *(const bf16x8*)(kB + 32);
;     const int cv0 = cb + (lane >> 3);
;     const bf16_t* vb = va + 8 * (lane & 7);
;     L.v0 = *(const u32x4*)(vb + (size_t)(rd + (min(max(cv0, 0), ncls - 1) << dsh)) * 64);
;     L.v1 = *(const u32x4*)(vb + (size_t)(rd + (min(max(cv0 + 8, 0), ncls - 1) << dsh)) * 64);
;     L.v2 = *(const u32x4*)(vb + (size_t)(rd + (min(max(cv0 + 16, 0), ncls - 1) << dsh)) * 64);
;     L.v3 = *(const u32x4*)(vb + (size_t)(rd + (min(max(cv0 + 24, 0), ncls - 1) << dsh)) * 64);
; __device__ __forceinline__ void attn_item(const bf16_t* __restrict__ Z, const bf16_t* __restrict__ KA, const bf16_t* __restrict__ VA, bf16_t* __restrict__ MIX, int S, int it) {
;     ...
;         for (int f = 18; f < 23; ++f) {
;             const AttnLd nxt0 = attn_load(ka, va, S, rt[0], n0, lane, f < 22 ? f + 1 : 22), nxt1 = attn_load(ka, va, S, rt[1], n0, lane, f < 22 ? f + 1 : 22);
;             const int cb = n0 - 64 + 32 * (f - 18), ncls = S >> 4, cq = n0 + qi;
;             f32x4 sA0 = {0.f, 0.f, 0.f, 0.f}, sB0 = {0.f, 0.f, 0.f, 0.f}, sA1 = {0.f, 0.f, 0.f, 0.f}, sB1 = {0.f, 0.f, 0.f, 0.f};
;             sA0 = MFMA16(cur0.ka0, q0[0], sA0); sA1 = MFMA16(cur1.ka0, q0[1], sA1); sB0 = MFMA16(cur0.kb0, q0[0], sB0); sB1 = MFMA16(cur1.kb0, q0[1], sB1);
;             sA0 = MFMA16(cur0.ka1, q1[0], sA0); sA1 = MFMA16(cur1.ka1, q1[1], sA1); sB0 = MFMA16(cur0.kb1, q1[0], sB0); sB1 = MFMA16(cur1.kb1, q1[1], sB1);
;             LDS_FENCE();
;             { bf16_t* d = Vs + (lane >> 3) * 68 + 8 * (lane & 7);
;               *(u32x2*)d = (u32x2){cur0.v0.x, cur0.v0.y}; *(u32x2*)(d + 4) = (u32x2){cur0.v0.z, cur0.v0.w};
.LBB0_401:
	s_cmpk_lg_i32 s15, 0x80
	s_cselect_b32 s19, s18, 22
	s_cmp_lt_u32 s19, 18
	s_cselect_b32 s20, 2, 4
	s_add_i32 s22, s19, -12
	s_cmp_lt_u32 s22, 6
	s_cselect_b32 s22, -12, 0xffffffee
	s_cmp_gt_u32 s19, 11
	s_cselect_b32 s20, s20, 0
	s_cselect_b32 s22, s22, 0
	s_add_i32 s22, s22, s19
	s_lshr_b32 s19, 16, s20
	s_mul_i32 s19, s19, s3
	s_lshl_b32 s22, s22, 5
	s_add_i32 s19, s19, s22
	v_ashrrev_i32_e32 v48, s20, v182
	s_sub_i32 s19, s19, 64
	v_add_u32_e32 v52, s19, v48
	s_lshr_b32 s23, s79, s20
	v_add_u32_e32 v48, v52, v220
	s_lshl_b32 s22, -1, s20
	v_max_i32_e32 v49, 0, v48
	s_add_i32 s23, s23, -1
	v_max_i32_e32 v48, -4, v48
	v_bitop3_b32 v53, v182, s22, v182 bitop3:0x30
	v_min_u32_e32 v49, s23, v49
	v_add_u32_e32 v48, 4, v48
	v_min_u32_e32 v50, s23, v48
	v_lshl_add_u32 v178, v49, s20, v53
	v_lshlrev_b64 v[48:49], 7, v[178:179]
	v_lshl_add_u32 v178, v50, s20, v53
	v_lshlrev_b64 v[50:51], 7, v[178:179]
	v_lshl_add_u64 v[48:49], v[190:191], 0, v[48:49]
	v_lshl_add_u64 v[50:51], v[190:191], 0, v[50:51]
	global_load_dwordx4 v[56:59], v[48:49], off
	global_load_dwordx4 v[60:63], v[48:49], off offset:64
	global_load_dwordx4 v[88:91], v[50:51], off
	global_load_dwordx4 v[92:95], v[50:51], off offset:64
	v_add_u32_e32 v50, v52, v221
	v_max_i32_e32 v48, 0, v50
	v_min_u32_e32 v48, s23, v48
	v_lshl_add_u32 v178, v48, s20, v53
	v_lshlrev_b64 v[48:49], 7, v[178:179]
	v_lshl_add_u64 v[48:49], v[188:189], 0, v[48:49]
	global_load_dwordx4 v[96:99], v[48:49], off
	v_max_i32_e32 v48, -8, v50
	v_add_u32_e32 v48, 8, v48
	v_min_u32_e32 v48, s23, v48
	v_lshl_add_u32 v178, v48, s20, v53
	v_lshlrev_b64 v[48:49], 7, v[178:179]
	v_lshl_add_u64 v[48:49], v[188:189], 0, v[48:49]
	global_load_dwordx4 v[100:103], v[48:49], off
	v_max_i32_e32 v48, -16, v50
	v_add_u32_e32 v48, 16, v48
	v_min_u32_e32 v48, s23, v48
	v_lshl_add_u32 v178, v48, s20, v53
	v_lshlrev_b64 v[48:49], 7, v[178:179]
	v_lshl_add_u64 v[48:49], v[188:189], 0, v[48:49]
	global_load_dwordx4 v[104:107], v[48:49], off
	v_max_i32_e32 v48, 0xffffffe8, v50
	v_add_u32_e32 v48, 24, v48
	v_min_u32_e32 v48, s23, v48
	v_lshl_add_u32 v178, v48, s20, v53
	v_lshlrev_b64 v[48:49], 7, v[178:179]
	v_lshl_add_u64 v[48:49], v[188:189], 0, v[48:49]
	global_load_dwordx4 v[108:111], v[48:49], off
	v_ashrrev_i32_e32 v48, s20, v180
	v_add_u32_e32 v72, s19, v48
	v_add_u32_e32 v48, v72, v220
	v_max_i32_e32 v49, 0, v48
	v_max_i32_e32 v48, -4, v48
	v_bitop3_b32 v84, v180, s22, v180 bitop3:0x30
	v_min_u32_e32 v49, s23, v49
	v_add_u32_e32 v48, 4, v48
	v_add_u32_e32 v85, v72, v221
	v_min_u32_e32 v50, s23, v48
	v_lshl_add_u32 v178, v49, s20, v84
	v_max_i32_e32 v72, 0, v85
	v_max_i32_e32 v76, -8, v85
	v_lshlrev_b64 v[48:49], 7, v[178:179]
	v_lshl_add_u32 v178, v50, s20, v84
	v_min_u32_e32 v72, s23, v72
	v_add_u32_e32 v76, 8, v76
	v_max_i32_e32 v80, -16, v85
	v_lshl_add_u64 v[52:53], v[190:191], 0, v[48:49]
	v_lshlrev_b64 v[48:49], 7, v[178:179]
	v_lshl_add_u32 v178, v72, s20, v84
	v_min_u32_e32 v76, s23, v76
	v_add_u32_e32 v80, 16, v80
	v_max_i32_e32 v85, 0xffffffe8, v85
	v_lshlrev_b64 v[72:73], 7, v[178:179]
	v_lshl_add_u32 v178, v76, s20, v84
	v_min_u32_e32 v80, s23, v80
	v_add_u32_e32 v85, 24, v85
	s_waitcnt vmcnt(21)
	v_mfma_f32_16x16x32_bf16 v[124:127], v[124:127], v[40:43], 0
	v_lshlrev_b64 v[76:77], 7, v[178:179]
	v_lshl_add_u32 v178, v80, s20, v84
	v_min_u32_e32 v85, s23, v85
	v_lshlrev_b64 v[80:81], 7, v[178:179]
	v_lshl_add_u32 v178, v85, s20, v84
	v_lshlrev_b64 v[84:85], 7, v[178:179]
	v_lshl_add_u64 v[68:69], v[190:191], 0, v[48:49]
	v_lshl_add_u64 v[72:73], v[188:189], 0, v[72:73]
	v_lshl_add_u64 v[76:77], v[188:189], 0, v[76:77]
	v_lshl_add_u64 v[80:81], v[188:189], 0, v[80:81]
	v_lshl_add_u64 v[84:85], v[188:189], 0, v[84:85]
	s_waitcnt vmcnt(20)
	v_mfma_f32_16x16x32_bf16 v[120:123], v[120:123], v[44:47], v[124:127]
	global_load_dwordx4 v[48:51], v[52:53], off
	s_nop 0
	global_load_dwordx4 v[52:55], v[52:53], off offset:64
	s_nop 0
	global_load_dwordx4 v[64:67], v[68:69], off
	s_nop 0
	global_load_dwordx4 v[68:71], v[68:69], off offset:64
	v_add_u32_e32 v124, 0x880, v222
	global_load_dwordx4 v[72:75], v[72:73], off
	v_mfma_f32_16x16x32_bf16 v[140:143], v[140:143], v[40:43], 0
	global_load_dwordx4 v[76:79], v[76:77], off
	v_mov_b32_e32 v226, v183
	global_load_dwordx4 v[80:83], v[80:81], off
	v_mfma_f32_16x16x32_bf16 v[136:139], v[136:139], v[44:47], v[140:143]
	global_load_dwordx4 v[84:87], v[84:85], off
	s_waitcnt lgkmcnt(0)
	s_waitcnt vmcnt(27)
	ds_write2_b64 v222, v[132:133], v[134:135] offset1:1
	s_waitcnt vmcnt(26)
	ds_write2_b64 v222, v[128:129], v[130:131] offset0:136 offset1:137
	s_waitcnt vmcnt(25)
	ds_write2_b64 v124, v[116:117], v[118:119] offset1:1
	v_add_u32_e32 v116, 0xcc0, v222
	s_waitcnt vmcnt(24)
	ds_write2_b64 v116, v[112:113], v[114:115] offset1:1
	v_add_u32_e32 v112, 0x8800, v222
	s_waitcnt vmcnt(19)
	ds_write2_b64 v112, v[156:157], v[158:159] offset1:1
	v_add_u32_e32 v112, 0x8c40, v222
	s_waitcnt vmcnt(18)
	ds_write2_b64 v112, v[148:149], v[150:151] offset1:1
	v_add_u32_e32 v112, 0x9080, v222
	s_waitcnt vmcnt(17)
	ds_write2_b64 v112, v[152:153], v[154:155] offset1:1
	v_add_u32_e32 v112, 0x94c0, v222
	s_waitcnt vmcnt(16)
; #define LDS_FENCE() asm volatile("s_waitcnt lgkmcnt(0)" ::: "memory")
; __device__ __forceinline__ bf16x8 attn_softmax_step(const f32x4& sA, const f32x4& sB, int cb, int cq, int ncls, int g, float& m, float& lsum, f32x4 (&O)[4]) {
;     float s[8]; bool ok[8];
;     const int c0v = cb + 8 * g, d0 = c0v - cq + 64;
; #pragma unroll
;     for (int j = 0; j < 8; ++j) {
;         ok[j] = ((unsigned)(c0v + j) < (unsigned)ncls) && ((unsigned)(d0 + j) <= 128u);
;         s[j] = ok[j] ? (j < 4 ? sA[j] : sB[j - 4]) : -__builtin_inff(); }
;     float mx = fmaxf(fmaxf(fmaxf(s[0], s[1]), fmaxf(s[2], s[3])), fmaxf(fmaxf(s[4], s[5]), fmaxf(s[6], s[7])));
;     mx = xmax32(xmax16(mx));
;     const float mn = fmaxf(m, mx), alpha = __builtin_amdgcn_exp2f(m - mn);
;     m = mn;
;     float pj[8], ps_ = 0.f;
; #pragma unroll
;     for (int j = 0; j < 8; ++j) { pj[j] = __builtin_amdgcn_exp2f(s[j] - mn); ps_ += pj[j]; }
;     lsum = lsum * alpha + ps_;
; #pragma unroll
;     for (int nbk = 0; nbk < 4; ++nbk) O[nbk] *= alpha;
;     return pack8(pj);
; __device__ __forceinline__ void attn_item(const bf16_t* __restrict__ Z, const bf16_t* __restrict__ KA, const bf16_t* __restrict__ VA, bf16_t* __restrict__ MIX, int S, int it) {
;     ...
;             LDS_FENCE();
;             { bf16_t* d = Vs + (lane >> 3) * 68 + 8 * (lane & 7);
;               *(u32x2*)d = (u32x2){cur0.v0.x, cur0.v0.y}; *(u32x2*)(d + 4) = (u32x2){cur0.v0.z, cur0.v0.w};
;               *(u32x2*)(d + 8 * 68) = (u32x2){cur0.v1.x, cur0.v1.y}; *(u32x2*)(d + 8 * 68 + 4) = (u32x2){cur0.v1.z, cur0.v1.w};
;               *(u32x2*)(d + 16 * 68) = (u32x2){cur0.v2.x, cur0.v2.y}; *(u32x2*)(d + 16 * 68 + 4) = (u32x2){cur0.v2.z, cur0.v2.w};
;               *(u32x2*)(d + 24 * 68) = (u32x2){cur0.v3.x, cur0.v3.y}; *(u32x2*)(d + 24 * 68 + 4) = (u32x2){cur0.v3.z, cur0.v3.w};
;               d = Vs1 + (lane >> 3) * 68 + 8 * (lane & 7);
;               *(u32x2*)d = (u32x2){cur1.v0.x, cur1.v0.y}; *(u32x2*)(d + 4) = (u32x2){cur1.v0.z, cur1.v0.w};
;               *(u32x2*)(d + 8 * 68) = (u32x2){cur1.v1.x, cur1.v1.y}; *(u32x2*)(d + 8 * 68 + 4) = (u32x2){cur1.v1.z, cur1.v1.w};
;               *(u32x2*)(d + 16 * 68) = (u32x2){cur1.v2.x, cur1.v2.y}; *(u32x2*)(d + 16 * 68 + 4) = (u32x2){cur1.v2.z, cur1.v2.w};
;               *(u32x2*)(d + 24 * 68) = (u32x2){cur1.v3.x, cur1.v3.y}; *(u32x2*)(d + 24 * 68 + 4) = (u32x2){cur1.v3.z, cur1.v3.w}; }
	ds_write2_b64 v112, v[144:145], v[146:147] offset1:1
	v_add_u32_e32 v112, s15, v224
	v_subrev_u32_e32 v113, 64, v112
	v_add_u32_e32 v114, s15, v225
	v_cmp_gt_u32_e32 vcc, s91, v113
	v_cmp_gt_u32_e64 s[36:37], s78, v114
	v_subrev_u32_e32 v115, 63, v112
	s_and_b64 vcc, vcc, s[36:37]
	v_cmp_gt_u32_e64 s[36:37], s91, v115
	v_add_u32_e32 v115, 1, v114
	v_cmp_gt_u32_e64 s[38:39], s78, v115
	v_subrev_u32_e32 v116, 62, v112
	s_and_b64 s[36:37], s[36:37], s[38:39]
	v_cmp_gt_u32_e64 s[38:39], s91, v116
	v_add_u32_e32 v116, 2, v114
	v_cmp_gt_u32_e64 s[40:41], s78, v116
	v_subrev_u32_e32 v116, 61, v112
	s_and_b64 s[38:39], s[38:39], s[40:41]
	v_cmp_gt_u32_e64 s[40:41], s91, v116
	v_add_u32_e32 v116, 3, v114
	v_cmp_gt_u32_e64 s[42:43], s78, v116
	v_subrev_u32_e32 v116, 60, v112
	s_and_b64 s[40:41], s[40:41], s[42:43]
	v_cmp_gt_u32_e64 s[42:43], s91, v116
	v_add_u32_e32 v116, 4, v114
	v_cmp_gt_u32_e64 s[44:45], s78, v116
	v_subrev_u32_e32 v116, 59, v112
	s_and_b64 s[42:43], s[42:43], s[44:45]
	v_cmp_gt_u32_e64 s[44:45], s91, v116
	v_add_u32_e32 v116, 5, v114
	v_cmp_gt_u32_e64 s[46:47], s78, v116
	v_subrev_u32_e32 v116, 58, v112
	s_and_b64 s[44:45], s[44:45], s[46:47]
	v_cmp_gt_u32_e64 s[46:47], s91, v116
	v_add_u32_e32 v116, 6, v114
	v_cmp_gt_u32_e64 s[48:49], s78, v116
	v_subrev_u32_e32 v112, 57, v112
	s_and_b64 s[46:47], s[46:47], s[48:49]
	v_cmp_gt_u32_e64 s[48:49], s91, v112
	v_add_u32_e32 v112, 7, v114
	v_cndmask_b32_e32 v113, v205, v136, vcc
	v_cndmask_b32_e64 v115, v205, v137, s[36:37]
	v_cmp_gt_u32_e64 s[50:51], s78, v112
	v_cndmask_b32_e64 v117, v205, v138, s[38:39]
	v_cndmask_b32_e64 v119, v205, v139, s[40:41]
	s_and_b64 s[48:49], s[48:49], s[50:51]
	v_cndmask_b32_e64 v125, v205, v122, s[46:47]
	v_cndmask_b32_e64 v112, v205, v123, s[48:49]
	v_max_f32_e32 v114, v113, v115
	v_cndmask_b32_e64 v124, v205, v120, s[42:43]
	v_max_f32_e32 v116, v117, v119
	v_cndmask_b32_e64 v121, v205, v121, s[44:45]
	v_max_f32_e32 v118, v125, v112
	v_max3_f32 v118, v124, v121, v118
	v_max3_f32 v114, v114, v116, v118
	v_mov_b32_e32 v116, v114
	s_nop 1
	v_permlane16_swap_b32_e32 v114, v116
	v_mfma_f32_16x16x32_bf16 v[172:175], v[172:175], v[0:3], 0
	v_max_f32_e32 v114, v114, v116
	v_mov_b32_e32 v116, v114
	s_nop 1
	v_permlane32_swap_b32_e32 v114, v116
	v_mfma_f32_16x16x32_bf16 v[164:167], v[164:167], v[0:3], 0
	v_max3_f32 v183, v226, v114, v116
	v_sub_f32_e32 v114, v226, v183
	v_sub_f32_e32 v113, v113, v183
	v_mfma_f32_16x16x32_bf16 v[140:143], v[168:171], v[4:7], v[172:175]
	v_exp_f32_e32 v116, v113
	v_sub_f32_e32 v113, v115, v183
	v_exp_f32_e32 v132, v114
	v_mfma_f32_16x16x32_bf16 v[160:163], v[160:163], v[4:7], v[164:167]
	v_exp_f32_e32 v118, v113
	v_sub_f32_e32 v113, v117, v183
	v_exp_f32_e32 v120, v113
	v_sub_f32_e32 v113, v119, v183
	v_exp_f32_e32 v122, v113
	v_sub_f32_e32 v113, v124, v183
	v_cndmask_b32_e32 v117, v205, v140, vcc
	v_cndmask_b32_e64 v119, v205, v141, s[36:37]
	v_exp_f32_e32 v124, v113
	v_sub_f32_e32 v113, v121, v183
	v_pk_mul_f32 v[30:31], v[30:31], v[132:133] op_sel_hi:[1,0]
	v_pk_mul_f32 v[28:29], v[28:29], v[132:133] op_sel_hi:[1,0]
	v_pk_mul_f32 v[26:27], v[26:27], v[132:133] op_sel_hi:[1,0]
	v_pk_mul_f32 v[24:25], v[24:25], v[132:133] op_sel_hi:[1,0]
	v_pk_mul_f32 v[34:35], v[34:35], v[132:133] op_sel_hi:[1,0]
	v_pk_mul_f32 v[32:33], v[32:33], v[132:133] op_sel_hi:[1,0]
	v_pk_mul_f32 v[38:39], v[38:39], v[132:133] op_sel_hi:[1,0]
	v_pk_mul_f32 v[36:37], v[36:37], v[132:133] op_sel_hi:[1,0]
	v_cndmask_b32_e64 v121, v205, v142, s[38:39]
	v_cndmask_b32_e64 v123, v205, v143, s[40:41]
	v_cndmask_b32_e64 v129, v205, v162, s[46:47]
	v_cndmask_b32_e64 v131, v205, v163, s[48:49]
	v_max_f32_e32 v133, v117, v119
	v_max_f32_e32 v134, v121, v123
	v_exp_f32_e32 v126, v113
	v_sub_f32_e32 v113, v125, v183
	v_cndmask_b32_e64 v125, v205, v160, s[42:43]
	v_cndmask_b32_e64 v127, v205, v161, s[44:45]
	v_max_f32_e32 v135, v129, v131
	v_max3_f32 v135, v125, v127, v135
	v_max3_f32 v133, v133, v134, v135
	v_mov_b32_e32 v134, v133
	s_nop 1
	v_permlane16_swap_b32_e32 v133, v134
	v_max_f32_e32 v133, v133, v134
	v_mov_b32_e32 v134, v133
	s_nop 1
	v_permlane32_swap_b32_e32 v133, v134
	v_mov_b32_e32 v135, v177
	v_max3_f32 v177, v135, v133, v134
	v_sub_f32_e32 v117, v117, v177
	v_exp_f32_e32 v117, v117
	v_sub_f32_e32 v119, v119, v177
	v_exp_f32_e32 v119, v119
	v_sub_f32_e32 v121, v121, v177
	v_sub_f32_e32 v133, v135, v177
	v_exp_f32_e32 v121, v121
	v_sub_f32_e32 v123, v123, v177
	v_exp_f32_e32 v123, v123
	v_sub_f32_e32 v125, v125, v177
	v_sub_f32_e32 v127, v127, v177
	v_exp_f32_e32 v133, v133
	v_exp_f32_e32 v125, v125
	v_exp_f32_e32 v127, v127
	v_pk_add_f32 v[134:135], v[116:117], 0 op_sel_hi:[1,0]
	v_sub_f32_e32 v112, v112, v183
	v_pk_add_f32 v[134:135], v[118:119], v[134:135]
	v_exp_f32_e32 v128, v113
	v_pk_add_f32 v[134:135], v[120:121], v[134:135]
	v_exp_f32_e32 v130, v112
	v_cvt_pk_bf16_f32 v112, v116, v118
	v_pk_add_f32 v[134:135], v[122:123], v[134:135]
	v_mov_b32_e32 v116, v133
	s_waitcnt lgkmcnt(0)
	v_cvt_pk_bf16_f32 v113, v120, v122
	v_cvt_pk_bf16_f32 v114, v124, v126
	v_pk_add_f32 v[134:135], v[124:125], v[134:135]
	v_pk_mul_f32 v[18:19], v[18:19], v[116:117] op_sel_hi:[1,0]
	v_pk_mul_f32 v[16:17], v[16:17], v[116:117] op_sel_hi:[1,0]
	v_pk_mul_f32 v[10:11], v[10:11], v[116:117] op_sel_hi:[1,0]
	v_pk_mul_f32 v[8:9], v[8:9], v[116:117] op_sel_hi:[1,0]
	v_pk_mul_f32 v[22:23], v[22:23], v[116:117] op_sel_hi:[1,0]
	v_pk_mul_f32 v[20:21], v[20:21], v[116:117] op_sel_hi:[1,0]
	v_pk_mul_f32 v[14:15], v[14:15], v[116:117] op_sel_hi:[1,0]
	v_pk_mul_f32 v[12:13], v[12:13], v[116:117] op_sel_hi:[1,0]
	v_cvt_pk_bf16_f32 v116, v117, v119
	v_cvt_pk_bf16_f32 v117, v121, v123
	v_cvt_pk_bf16_f32 v118, v125, v127
	ds_read_b64_tr_b16 v[122:123], v223 offset:544
	ds_read_b64_tr_b16 v[120:121], v223
	ds_read_b64_tr_b16 v[124:125], v223 offset:32
	v_cvt_pk_bf16_f32 v115, v128, v130
	v_sub_f32_e32 v129, v129, v177
	v_sub_f32_e32 v131, v131, v177
	v_exp_f32_e32 v129, v129
	v_exp_f32_e32 v131, v131
	s_waitcnt lgkmcnt(1)
; #define LDS_FENCE() asm volatile("s_waitcnt lgkmcnt(0)" ::: "memory")
; #define MFMA16(a, b, c) __builtin_amdgcn_mfma_f32_16x16x32_bf16((a), (b), (c), 0, 0, 0)
; template <int NROWS>
; __device__ __forceinline__ void attn_stage(const bf16_t* __restrict__ ka, const bf16_t* __restrict__ va, bf16_t* Kt, bf16_t* Vt, int c0, int ncls, int rd, int dsh, int tid) {
;     constexpr int IT = (NROWS * 16 + NTHR - 1) / NTHR;
;     u32x4 v[IT];
; #pragma unroll
;     for (int u = 0; u < IT; ++u) { const int idx = min(tid + u * NTHR, NROWS * 16 - 1);
;         const int i = idx >> 4, ch = idx & 15, isv = ch >> 3, c8 = ch & 7; const int c = min(max(c0 + i, 0), ncls - 1);
;         v[u] = *(const u32x4*)((isv ? va : ka) + (size_t)(rd + (c << dsh)) * 64 + 8 * c8); }
; __device__ __forceinline__ void attn_item(const bf16_t* __restrict__ Z, const bf16_t* __restrict__ KA, const bf16_t* __restrict__ VA, bf16_t* __restrict__ MIX, int S, int it) {
;     ...
;             LDS_FENCE();
; #pragma unroll
;             for (int nbk = 0; nbk < 4; ++nbk) { O[0][nbk] = MFMA16(gather8(Vs + (8 * g) * 68 + 16 * nbk, 68, qi), P0_, O[0][nbk]); O[1][nbk] = MFMA16(gather8(Vs1 + (8 * g) * 68 + 16 * nbk, 68, qi), P1_, O[1][nbk]); }
;             cur0 = nxt0; cur1 = nxt1;
;         }
	v_mfma_f32_16x16x32_bf16 v[28:31], v[120:123], v[112:115], v[28:31]
	ds_read_b64_tr_b16 v[120:121], v223 offset:34816
	ds_read_b64_tr_b16 v[122:123], v223 offset:35360
	v_pk_add_f32 v[134:135], v[126:127], v[134:135]
	v_cvt_pk_bf16_f32 v119, v129, v131
	ds_read_b64_tr_b16 v[126:127], v223 offset:576
	s_waitcnt lgkmcnt(0)
	v_mfma_f32_16x16x32_bf16 v[24:27], v[124:127], v[112:115], v[24:27]
	v_add_f32_e64 v134, v128, v134
	v_add_f32_e64 v135, v129, v135
	s_add_i32 s15, s15, 32
	v_pk_add_f32 v[134:135], v[130:131], v[134:135]
	v_mfma_f32_16x16x32_bf16 v[16:19], v[120:123], v[116:119], v[16:19]
	ds_read_b64_tr_b16 v[120:121], v223 offset:34848
	ds_read_b64_tr_b16 v[122:123], v223 offset:35392
	v_pk_fma_f32 v[184:185], v[184:185], v[132:133], v[134:135]
	s_add_i32 s18, s18, 1
	s_waitcnt lgkmcnt(0)
	v_mfma_f32_16x16x32_bf16 v[8:11], v[120:123], v[116:119], v[8:11]
	ds_read_b64_tr_b16 v[120:121], v223 offset:64
	ds_read_b64_tr_b16 v[122:123], v223 offset:608
	s_waitcnt vmcnt(10)
	v_mov_b64_e32 v[130:131], v[102:103]
	v_mov_b64_e32 v[134:135], v[98:99]
	s_waitcnt lgkmcnt(0)
	v_mfma_f32_16x16x32_bf16 v[32:35], v[120:123], v[112:115], v[32:35]
	ds_read_b64_tr_b16 v[120:121], v223 offset:34880
	ds_read_b64_tr_b16 v[122:123], v223 offset:35424
	v_mov_b64_e32 v[126:127], v[90:91]
	v_mov_b64_e32 v[138:139], v[62:63]
	s_waitcnt lgkmcnt(0)
	v_mfma_f32_16x16x32_bf16 v[20:23], v[120:123], v[116:119], v[20:23]
	ds_read_b64_tr_b16 v[120:121], v223 offset:96
	ds_read_b64_tr_b16 v[122:123], v223 offset:640
	v_mov_b64_e32 v[142:143], v[58:59]
	s_waitcnt vmcnt(0)
	v_mov_b64_e32 v[146:147], v[86:87]
	s_waitcnt lgkmcnt(0)
	v_mfma_f32_16x16x32_bf16 v[36:39], v[120:123], v[112:115], v[36:39]
	ds_read_b64_tr_b16 v[112:113], v223 offset:34912
	ds_read_b64_tr_b16 v[114:115], v223 offset:35456
	v_mov_b64_e32 v[122:123], v[94:95]
	v_mov_b64_e32 v[154:155], v[82:83]
	s_waitcnt lgkmcnt(0)
	v_mfma_f32_16x16x32_bf16 v[12:15], v[112:115], v[116:119], v[12:15]
	v_mov_b64_e32 v[114:115], v[110:111]
	v_mov_b64_e32 v[118:119], v[106:107]
	v_mov_b64_e32 v[150:151], v[78:79]
	v_mov_b64_e32 v[158:159], v[74:75]
	v_mov_b64_e32 v[162:163], v[70:71]
	v_mov_b64_e32 v[166:167], v[66:67]
	v_mov_b64_e32 v[170:171], v[54:55]
	v_mov_b64_e32 v[174:175], v[50:51]
	s_cmpk_eq_i32 s15, 0xa0
	v_mov_b64_e32 v[112:113], v[108:109]
	v_mov_b64_e32 v[116:117], v[104:105]
	v_mov_b64_e32 v[128:129], v[100:101]
	v_mov_b64_e32 v[132:133], v[96:97]
	v_mov_b64_e32 v[120:121], v[92:93]
	v_mov_b64_e32 v[124:125], v[88:89]
	v_mov_b64_e32 v[136:137], v[60:61]
	v_mov_b64_e32 v[140:141], v[56:57]
	v_mov_b64_e32 v[144:145], v[84:85]
	v_mov_b64_e32 v[152:153], v[80:81]
	v_mov_b64_e32 v[148:149], v[76:77]
	v_mov_b64_e32 v[156:157], v[72:73]
	v_mov_b64_e32 v[160:161], v[68:69]
	v_mov_b64_e32 v[164:165], v[64:65]
	v_mov_b64_e32 v[168:169], v[52:53]
	v_mov_b64_e32 v[172:173], v[48:49]
	s_cbranch_scc0 .LBB0_401
	v_min_i32_e32 v52, 0x18ff, v187
	s_sub_i32 s3, s12, 64
	v_ashrrev_i32_e32 v124, 4, v52
	v_add_u32_e32 v48, s3, v124
	v_max_i32_e32 v48, 0, v48
	v_and_b32_e32 v125, 8, v52
	v_min_u32_e32 v178, s90, v48
	v_mov_b32_e32 v99, s95
	v_mov_b32_e32 v100, s7
	v_cmp_eq_u32_e32 vcc, 0, v125
	v_mov_b32_e32 v122, s94
	v_mov_b32_e32 v123, s6
	v_cndmask_b32_e32 v49, v99, v100, vcc
	v_cndmask_b32_e32 v48, v122, v123, vcc
	v_lshlrev_b64 v[50:51], 7, v[178:179]
	v_min_i32_e32 v56, 0x16ff, v187
	v_lshl_add_u64 v[48:49], v[48:49], 0, v[50:51]
	v_lshlrev_b32_e32 v50, 4, v52
	v_add_u32_e32 v52, 0x200, v56
	v_ashrrev_i32_e32 v126, 4, v52
	v_add_u32_e32 v52, s3, v126
	v_max_i32_e32 v52, 0, v52
	v_and_b32_e32 v127, 8, v56
	v_min_u32_e32 v52, s90, v52
	v_cmp_eq_u32_e64 s[36:37], 0, v127
	v_mov_b32_e32 v53, v179
	v_lshlrev_b64 v[52:53], 7, v[52:53]
	v_cndmask_b32_e64 v55, v99, v100, s[36:37]
	v_cndmask_b32_e64 v54, v122, v123, s[36:37]
	v_lshl_add_u64 v[52:53], v[54:55], 0, v[52:53]
	v_lshlrev_b32_e32 v54, 4, v56
	v_and_b32_e32 v56, 0x70, v54
	v_mov_b32_e32 v57, v179
	v_lshl_add_u64 v[52:53], v[52:53], 0, v[56:57]
	v_min_i32_e32 v57, 0x14ff, v187
	v_add_u32_e32 v58, 0x400, v57
	v_ashrrev_i32_e32 v128, 4, v58
	v_add_u32_e32 v58, s3, v128
	v_max_i32_e32 v58, 0, v58
	v_and_b32_e32 v129, 8, v57
	v_min_u32_e32 v58, s90, v58
	v_cmp_eq_u32_e64 s[38:39], 0, v129
	v_mov_b32_e32 v59, v179
	v_lshlrev_b32_e32 v57, 4, v57
	v_cndmask_b32_e64 v61, v99, v100, s[38:39]
	v_cndmask_b32_e64 v60, v122, v123, s[38:39]
	v_lshlrev_b64 v[58:59], 7, v[58:59]
	v_and_b32_e32 v102, 0x70, v57
	v_min_i32_e32 v57, 0x12ff, v187
	v_lshl_add_u64 v[58:59], v[60:61], 0, v[58:59]
	v_mov_b32_e32 v103, v179
	v_add_u32_e32 v62, 0x600, v57
	v_lshl_add_u64 v[58:59], v[58:59], 0, v[102:103]
	v_ashrrev_i32_e32 v103, 4, v62
	v_add_u32_e32 v62, s3, v103
	v_max_i32_e32 v62, 0, v62
	v_and_b32_e32 v130, 8, v57
	v_min_u32_e32 v62, s90, v62
	v_cmp_eq_u32_e64 s[40:41], 0, v130
	v_mov_b32_e32 v63, v179
	v_lshlrev_b32_e32 v57, 4, v57
	v_cndmask_b32_e64 v65, v99, v100, s[40:41]
	v_cndmask_b32_e64 v64, v122, v123, s[40:41]
	v_lshlrev_b64 v[62:63], 7, v[62:63]
	v_and_b32_e32 v104, 0x70, v57
	v_min_i32_e32 v57, 0x10ff, v187
	v_lshl_add_u64 v[62:63], v[64:65], 0, v[62:63]
	v_mov_b32_e32 v105, v179
	v_add_u32_e32 v66, 0x800, v57
	v_lshl_add_u64 v[62:63], v[62:63], 0, v[104:105]
	v_ashrrev_i32_e32 v105, 4, v66
	v_add_u32_e32 v66, s3, v105
	v_max_i32_e32 v66, 0, v66
	v_and_b32_e32 v131, 8, v57
	v_min_u32_e32 v66, s90, v66
	v_cmp_eq_u32_e64 s[42:43], 0, v131
	v_mov_b32_e32 v67, v179
	v_lshlrev_b32_e32 v57, 4, v57
	v_cndmask_b32_e64 v69, v99, v100, s[42:43]
	v_cndmask_b32_e64 v68, v122, v123, s[42:43]
	v_lshlrev_b64 v[66:67], 7, v[66:67]
	v_and_b32_e32 v106, 0x70, v57
	v_min_i32_e32 v57, 0xeff, v187
	v_lshl_add_u64 v[66:67], v[68:69], 0, v[66:67]
	v_mov_b32_e32 v107, v179
	v_add_u32_e32 v70, 0xa00, v57
	v_lshl_add_u64 v[66:67], v[66:67], 0, v[106:107]
	v_ashrrev_i32_e32 v107, 4, v70
	v_add_u32_e32 v70, s3, v107
	v_max_i32_e32 v70, 0, v70
	v_and_b32_e32 v132, 8, v57
	v_min_u32_e32 v70, s90, v70
	v_cmp_eq_u32_e64 s[44:45], 0, v132
	v_mov_b32_e32 v71, v179
	v_lshlrev_b32_e32 v57, 4, v57
	v_cndmask_b32_e64 v73, v99, v100, s[44:45]
	v_cndmask_b32_e64 v72, v122, v123, s[44:45]
	v_lshlrev_b64 v[70:71], 7, v[70:71]
	v_and_b32_e32 v108, 0x70, v57
	v_min_i32_e32 v57, 0xcff, v187
	v_lshl_add_u64 v[70:71], v[72:73], 0, v[70:71]
	v_mov_b32_e32 v109, v179
	v_add_u32_e32 v74, 0xc00, v57
	v_lshl_add_u64 v[70:71], v[70:71], 0, v[108:109]
	v_ashrrev_i32_e32 v109, 4, v74
	v_add_u32_e32 v74, s3, v109
	v_and_b32_e32 v178, 0x70, v50
	v_max_i32_e32 v74, 0, v74
	v_and_b32_e32 v133, 8, v57
	v_lshl_add_u64 v[48:49], v[48:49], 0, v[178:179]
	v_min_u32_e32 v74, s90, v74
	v_cmp_eq_u32_e64 s[46:47], 0, v133
	v_mov_b32_e32 v75, v179
	v_lshlrev_b32_e32 v57, 4, v57
	s_waitcnt lgkmcnt(0)
	s_barrier
; template <int NROWS>
; __device__ __forceinline__ void attn_stage(const bf16_t* __restrict__ ka, const bf16_t* __restrict__ va, bf16_t* Kt, bf16_t* Vt, int c0, int ncls, int rd, int dsh, int tid) {
;     ...
;     for (int u = 0; u < IT; ++u) { const int idx = min(tid + u * NTHR, NROWS * 16 - 1);
;         const int i = idx >> 4, ch = idx & 15, isv = ch >> 3, c8 = ch & 7; const int c = min(max(c0 + i, 0), ncls - 1);
;         v[u] = *(const u32x4*)((isv ? va : ka) + (size_t)(rd + (c << dsh)) * 64 + 8 * c8); }
; #pragma unroll
;     for (int u = 0; u < IT; ++u) { const int idx = min(tid + u * NTHR, NROWS * 16 - 1);
;         const int i = idx >> 4, ch = idx & 15, isv = ch >> 3, c8 = ch & 7;
;         bf16_t* d = isv ? (Vt + i * 68 + 8 * c8) : (Kt + i * 72 + 8 * c8);
;         *(u32x2*)d = (u32x2){v[u].x, v[u].y}; *(u32x2*)(d + 4) = (u32x2){v[u].z, v[u].w}; }
	global_load_dwordx4 v[48:51], v[48:49], off
	v_cndmask_b32_e64 v77, v99, v100, s[46:47]
	v_cndmask_b32_e64 v76, v122, v123, s[46:47]
	v_lshlrev_b64 v[74:75], 7, v[74:75]
	v_and_b32_e32 v110, 0x70, v57
	v_min_i32_e32 v57, 0xaff, v187
	v_lshl_add_u64 v[74:75], v[76:77], 0, v[74:75]
	v_mov_b32_e32 v111, v179
	v_add_u32_e32 v78, 0xe00, v57
	v_lshl_add_u64 v[74:75], v[74:75], 0, v[110:111]
	v_ashrrev_i32_e32 v111, 4, v78
	global_load_dwordx4 v[52:55], v[52:53], off
	v_add_u32_e32 v78, s3, v111
	v_max_i32_e32 v78, 0, v78
	v_and_b32_e32 v134, 8, v57
	v_min_u32_e32 v78, s90, v78
	v_cmp_eq_u32_e64 s[48:49], 0, v134
	v_mov_b32_e32 v79, v179
	v_lshlrev_b32_e32 v57, 4, v57
	global_load_dwordx4 v[58:61], v[58:59], off
	v_cndmask_b32_e64 v81, v99, v100, s[48:49]
	v_cndmask_b32_e64 v80, v122, v123, s[48:49]
	v_lshlrev_b64 v[78:79], 7, v[78:79]
	v_and_b32_e32 v112, 0x70, v57
	v_min_i32_e32 v57, 0x8ff, v187
	v_lshl_add_u64 v[78:79], v[80:81], 0, v[78:79]
	v_mov_b32_e32 v113, v179
	v_add_u32_e32 v82, 0x1000, v57
	v_lshl_add_u64 v[78:79], v[78:79], 0, v[112:113]
	v_ashrrev_i32_e32 v113, 4, v82
	global_load_dwordx4 v[62:65], v[62:63], off
	v_add_u32_e32 v82, s3, v113
	v_max_i32_e32 v82, 0, v82
	v_and_b32_e32 v135, 8, v57
	v_min_u32_e32 v82, s90, v82
	v_cmp_eq_u32_e64 s[50:51], 0, v135
	v_mov_b32_e32 v83, v179
	v_lshlrev_b32_e32 v57, 4, v57
	global_load_dwordx4 v[66:69], v[66:67], off
	v_cndmask_b32_e64 v85, v99, v100, s[50:51]
	v_cndmask_b32_e64 v84, v122, v123, s[50:51]
	v_lshlrev_b64 v[82:83], 7, v[82:83]
	v_and_b32_e32 v114, 0x70, v57
	v_min_i32_e32 v57, 0x6ff, v187
	v_lshl_add_u64 v[82:83], v[84:85], 0, v[82:83]
	v_mov_b32_e32 v115, v179
	v_add_u32_e32 v86, 0x1200, v57
	v_lshl_add_u64 v[82:83], v[82:83], 0, v[114:115]
	v_ashrrev_i32_e32 v115, 4, v86
	global_load_dwordx4 v[70:73], v[70:71], off
	v_add_u32_e32 v86, s3, v115
	v_max_i32_e32 v86, 0, v86
	v_and_b32_e32 v136, 8, v57
	v_min_u32_e32 v86, s90, v86
	v_cmp_eq_u32_e64 s[52:53], 0, v136
	v_mov_b32_e32 v87, v179
	v_lshlrev_b32_e32 v57, 4, v57
	global_load_dwordx4 v[74:77], v[74:75], off
	v_cndmask_b32_e64 v89, v99, v100, s[52:53]
	v_cndmask_b32_e64 v88, v122, v123, s[52:53]
	v_lshlrev_b64 v[86:87], 7, v[86:87]
	v_and_b32_e32 v116, 0x70, v57
	v_min_i32_e32 v57, 0x4ff, v187
	v_lshl_add_u64 v[86:87], v[88:89], 0, v[86:87]
	v_mov_b32_e32 v117, v179
	v_add_u32_e32 v90, 0x1400, v57
	v_lshl_add_u64 v[86:87], v[86:87], 0, v[116:117]
	v_ashrrev_i32_e32 v117, 4, v90
	global_load_dwordx4 v[78:81], v[78:79], off
	v_add_u32_e32 v90, s3, v117
	v_max_i32_e32 v90, 0, v90
	v_and_b32_e32 v137, 8, v57
	v_min_u32_e32 v90, s90, v90
	v_cmp_eq_u32_e64 s[54:55], 0, v137
	v_mov_b32_e32 v91, v179
	v_lshlrev_b32_e32 v57, 4, v57
	global_load_dwordx4 v[82:85], v[82:83], off
	v_cndmask_b32_e64 v93, v99, v100, s[54:55]
	v_cndmask_b32_e64 v92, v122, v123, s[54:55]
	v_lshlrev_b64 v[90:91], 7, v[90:91]
	v_and_b32_e32 v118, 0x70, v57
	v_min_i32_e32 v57, 0x2ff, v187
	v_lshl_add_u64 v[90:91], v[92:93], 0, v[90:91]
	v_mov_b32_e32 v119, v179
	v_add_u32_e32 v94, 0x1600, v57
	v_lshl_add_u64 v[90:91], v[90:91], 0, v[118:119]
	v_ashrrev_i32_e32 v119, 4, v94
	global_load_dwordx4 v[86:89], v[86:87], off
	v_add_u32_e32 v94, s3, v119
	v_max_i32_e32 v94, 0, v94
	v_and_b32_e32 v138, 8, v57
	v_min_u32_e32 v94, s90, v94
	v_cmp_eq_u32_e64 s[56:57], 0, v138
	v_mov_b32_e32 v95, v179
	global_load_dwordx4 v[90:93], v[90:91], off
	v_cndmask_b32_e64 v97, v99, v100, s[56:57]
	v_cndmask_b32_e64 v96, v122, v123, s[56:57]
	v_lshlrev_b64 v[94:95], 7, v[94:95]
	v_lshlrev_b32_e32 v57, 4, v57
	v_lshl_add_u64 v[94:95], v[96:97], 0, v[94:95]
	v_and_b32_e32 v120, 0x70, v57
	v_mov_b32_e32 v121, v179
	v_min_i32_e32 v57, 0xff, v187
	v_lshl_add_u64 v[94:95], v[94:95], 0, v[120:121]
	v_add_u32_e32 v98, 0x1800, v57
	global_load_dwordx4 v[94:97], v[94:95], off
	v_ashrrev_i32_e32 v121, 4, v98
	v_add_u32_e32 v98, s3, v121
	v_and_b32_e32 v139, 8, v57
	v_max_i32_e32 v98, 0, v98
	v_cmp_eq_u32_e64 s[58:59], 0, v139
	v_min_u32_e32 v98, s90, v98
	v_lshlrev_b32_e32 v57, 4, v57
	v_cndmask_b32_e64 v101, v99, v100, s[58:59]
	v_mov_b32_e32 v99, v179
	v_cndmask_b32_e64 v100, v122, v123, s[58:59]
	v_lshlrev_b64 v[98:99], 7, v[98:99]
	v_lshl_add_u64 v[98:99], v[100:101], 0, v[98:99]
	v_and_b32_e32 v122, 0x70, v57
	v_mov_b32_e32 v123, v179
	v_lshl_add_u64 v[98:99], v[98:99], 0, v[122:123]
	global_load_dwordx4 v[98:101], v[98:99], off
	v_readlane_b32 s15, v255, 0
	v_sub_u32_e32 v57, 0x90, v125
	v_mul_lo_u32 v57, v57, v124
	v_mov_b32_e32 v123, s15
	v_cndmask_b32_e64 v125, v123, 0, vcc
	v_add3_u32 v57, v125, v57, v178
	s_waitcnt vmcnt(12)
	ds_write2_b64 v57, v[48:49], v[50:51] offset1:1
	v_sub_u32_e32 v48, 0x90, v127
	v_cndmask_b32_e64 v49, v123, 0, s[36:37]
	v_mul_lo_u32 v48, v126, v48
	v_add3_u32 v48, v49, v48, v56
	s_waitcnt vmcnt(11)
	ds_write2_b64 v48, v[52:53], v[54:55] offset1:1
	v_sub_u32_e32 v48, 0x90, v129
	v_cndmask_b32_e64 v49, v123, 0, s[38:39]
	v_mul_lo_u32 v48, v128, v48
	v_add3_u32 v48, v49, v48, v102
	s_waitcnt vmcnt(10)
	ds_write2_b64 v48, v[58:59], v[60:61] offset1:1
	v_sub_u32_e32 v48, 0x90, v130
	v_cndmask_b32_e64 v49, v123, 0, s[40:41]
	v_mul_lo_u32 v48, v103, v48
	v_add3_u32 v48, v49, v48, v104
	s_waitcnt vmcnt(9)
	ds_write2_b64 v48, v[62:63], v[64:65] offset1:1
	v_sub_u32_e32 v48, 0x90, v131
	v_cndmask_b32_e64 v49, v123, 0, s[42:43]
	v_mul_lo_u32 v48, v105, v48
	v_add3_u32 v48, v49, v48, v106
	s_waitcnt vmcnt(8)
	ds_write2_b64 v48, v[66:67], v[68:69] offset1:1
	v_sub_u32_e32 v48, 0x90, v132
	v_cndmask_b32_e64 v49, v123, 0, s[44:45]
	v_mul_lo_u32 v48, v107, v48
	v_add3_u32 v48, v49, v48, v108
	s_waitcnt vmcnt(7)
; #define MFMA16(a, b, c) __builtin_amdgcn_mfma_f32_16x16x32_bf16((a), (b), (c), 0, 0, 0)
; __device__ __forceinline__ bf16x8 attn_softmax_step(const f32x4& sA, const f32x4& sB, int cb, int cq, int ncls, int g, float& m, float& lsum, f32x4 (&O)[4]) {
;     float s[8]; bool ok[8];
;     const int c0v = cb + 8 * g, d0 = c0v - cq + 64;
; #pragma unroll
;     for (int j = 0; j < 8; ++j) {
;         ok[j] = ((unsigned)(c0v + j) < (unsigned)ncls) && ((unsigned)(d0 + j) <= 128u);
;         s[j] = ok[j] ? (j < 4 ? sA[j] : sB[j - 4]) : -__builtin_inff(); }
;     float mx = fmaxf(fmaxf(fmaxf(s[0], s[1]), fmaxf(s[2], s[3])), fmaxf(fmaxf(s[4], s[5]), fmaxf(s[6], s[7])));
;     mx = xmax32(xmax16(mx));
;     const float mn = fmaxf(m, mx), alpha = __builtin_amdgcn_exp2f(m - mn);
;     m = mn;
;     float pj[8], ps_ = 0.f;
; #pragma unroll
;     for (int j = 0; j < 8; ++j) { pj[j] = __builtin_amdgcn_exp2f(s[j] - mn); ps_ += pj[j]; }
;     lsum = lsum * alpha + ps_;
; #pragma unroll
;     for (int nbk = 0; nbk < 4; ++nbk) O[nbk] *= alpha;
;     return pack8(pj);
; }
; __device__ __forceinline__ void attn_lds_step(const bf16_t* Kt, const bf16_t* Vt, int rowb, const bf16x8& q0, const bf16x8& q1, int cb, int cq, int ncls,
;                                               int qi, int g, float& m, float& lsum, f32x4 (&O)[4]) {
;     const bf16_t* kA = Kt + (rowb + 8 * (qi >> 2) + (qi & 3)) * 72 + 8 * g;
;     const bf16x8 ka0 = *(const bf16x8*)kA, ka1 = *(const bf16x8*)(kA + 32), kb0 = *(const bf16x8*)(kA + 4 * 72), kb1 = *(const bf16x8*)(kA + 4 * 72 + 32);
;     f32x4 sA = {0.f, 0.f, 0.f, 0.f}, sB = {0.f, 0.f, 0.f, 0.f};
;     sA = MFMA16(ka0, q0, sA); sA = MFMA16(ka1, q1, sA);
;     sB = MFMA16(kb0, q0, sB); sB = MFMA16(kb1, q1, sB);
;     const bf16x8 P = attn_softmax_step(sA, sB, cb, cq, ncls, g, m, lsum, O);
; #pragma unroll
;     for (int nbk = 0; nbk < 4; ++nbk) O[nbk] = MFMA16(gather8(Vt + (rowb + 8 * g) * 68 + 16 * nbk, 68, qi), P, O[nbk]);
; }
; __device__ __forceinline__ void attn_item(const bf16_t* __restrict__ Z, const bf16_t* __restrict__ KA, const bf16_t* __restrict__ VA, bf16_t* __restrict__ MIX, int S, int it) {
;     ...
; #pragma unroll 1
;     for (int i2 = 0; i2 < 12; ++i2) {
;         attn_lds_step(Kt, Vt, rt[0] + 32 * i2, q0[0], q1[0], P0 + rt[0] - 64 + 32 * i2, P0 + rt[0] + 16 * qi, S, qi, g, m[0], lsum[0], O[0]);
	ds_write2_b64 v48, v[70:71], v[72:73] offset1:1
	v_sub_u32_e32 v48, 0x90, v133
	v_cndmask_b32_e64 v49, v123, 0, s[46:47]
	v_mul_lo_u32 v48, v109, v48
	v_add3_u32 v48, v49, v48, v110
	s_waitcnt vmcnt(6)
	ds_write2_b64 v48, v[74:75], v[76:77] offset1:1
	v_sub_u32_e32 v48, 0x90, v134
	v_cndmask_b32_e64 v49, v123, 0, s[48:49]
	v_mul_lo_u32 v48, v111, v48
	v_add3_u32 v48, v49, v48, v112
	s_waitcnt vmcnt(5)
	ds_write2_b64 v48, v[78:79], v[80:81] offset1:1
	v_sub_u32_e32 v48, 0x90, v135
	v_cndmask_b32_e64 v49, v123, 0, s[50:51]
	v_mul_lo_u32 v48, v113, v48
	v_add3_u32 v48, v49, v48, v114
	s_waitcnt vmcnt(4)
	ds_write2_b64 v48, v[82:83], v[84:85] offset1:1
	v_sub_u32_e32 v48, 0x90, v136
	v_cndmask_b32_e64 v49, v123, 0, s[52:53]
	v_mul_lo_u32 v48, v115, v48
	v_add3_u32 v48, v49, v48, v116
	s_waitcnt vmcnt(3)
	ds_write2_b64 v48, v[86:87], v[88:89] offset1:1
	v_sub_u32_e32 v48, 0x90, v137
	v_cndmask_b32_e64 v49, v123, 0, s[54:55]
	v_mul_lo_u32 v48, v117, v48
	v_add3_u32 v48, v49, v48, v118
	s_waitcnt vmcnt(2)
	ds_write2_b64 v48, v[90:91], v[92:93] offset1:1
	v_sub_u32_e32 v48, 0x90, v138
	v_cndmask_b32_e64 v49, v123, 0, s[56:57]
	v_mul_lo_u32 v48, v119, v48
	v_add3_u32 v48, v49, v48, v120
	v_cndmask_b32_e64 v49, v123, 0, s[58:59]
	s_movk_i32 s15, 0x220
	s_waitcnt vmcnt(1)
	ds_write2_b64 v48, v[94:95], v[96:97] offset1:1
	v_sub_u32_e32 v48, 0x90, v139
	v_mul_lo_u32 v48, v121, v48
	v_add3_u32 v48, v49, v48, v122
	v_lshrrev_b32_e32 v49, 2, v217
	v_mul_u32_u24_e32 v94, 0x440, v218
	v_mul_lo_u32 v50, v49, s15
	v_mul_u32_u24_e32 v51, 0x88, v211
	v_add3_u32 v50, v94, v50, v51
	v_lshlrev_b32_e32 v96, 3, v212
	v_add3_u32 v76, v50, v96, v219
	s_movk_i32 s15, 0x240
	v_add_u32_e32 v50, v211, v212
	v_mul_u32_u24_e32 v95, 0x480, v214
	v_mul_lo_u32 v49, v49, s15
	v_mul_u32_u24_e32 v51, 0x90, v50
	s_waitcnt vmcnt(0)
	ds_write2_b64 v48, v[98:99], v[100:101] offset1:1
	v_lshlrev_b32_e32 v48, 1, v215
	v_add3_u32 v49, v95, v49, v51
	v_lshlrev_b32_e32 v52, 4, v218
	s_movk_i32 s15, 0x120
	v_and_b32_e32 v53, 24, v48
	v_add3_u32 v48, v186, v216, v211
	v_add3_u32 v77, v49, v52, s15
	s_movk_i32 s15, 0x88
	v_add_u32_e32 v74, s12, v48
	v_mul_lo_u32 v48, v48, s15
	v_add3_u32 v78, v48, v96, v219
	v_add3_u32 v48, v53, v216, v50
	s_movk_i32 s15, 0x90
	s_mov_b32 s3, 0
	v_mad_i32_i24 v75, v215, -16, v186
	v_mad_u64_u32 v[54:55], s[18:19], v48, s15, v[52:53]
	s_waitcnt lgkmcnt(0)
	s_barrier
.LBB0_403:
	v_add_u32_e32 v55, 0, v54
	ds_read_b128 v[48:51], v55
	ds_read_b128 v[56:59], v55 offset:64
	ds_read_b128 v[60:63], v55 offset:576
	ds_read_b128 v[64:67], v55 offset:640
	v_add_u32_e32 v55, s3, v74
	s_waitcnt lgkmcnt(3)
	v_mfma_f32_16x16x32_bf16 v[48:51], v[48:51], v[40:43], 0
	v_mov_b32_e32 v68, v183
	v_add_u32_e32 v54, 0x1200, v54
	s_waitcnt lgkmcnt(2)
	v_mfma_f32_16x16x32_bf16 v[48:51], v[56:59], v[44:47], v[48:51]
	s_waitcnt lgkmcnt(1)
	v_mfma_f32_16x16x32_bf16 v[56:59], v[60:63], v[40:43], 0
	v_subrev_u32_e32 v60, 64, v55
	v_add_u32_e32 v61, s3, v75
	v_cmp_gt_u32_e64 s[36:37], s79, v60
	v_cmp_gt_u32_e32 vcc, s78, v61
	s_and_b64 s[36:37], s[36:37], vcc
	v_cmp_gt_u32_e64 s[38:39], s90, v60
	v_add_u32_e32 v60, 1, v61
	v_cndmask_b32_e64 v48, v205, v48, s[36:37]
	v_cmp_gt_u32_e64 s[36:37], s78, v60
	v_subrev_u32_e32 v60, 62, v55
	s_and_b64 s[38:39], s[38:39], s[36:37]
	v_cmp_gt_u32_e64 s[40:41], s79, v60
	v_add_u32_e32 v60, 2, v61
	v_cndmask_b32_e64 v49, v205, v49, s[38:39]
	v_cmp_gt_u32_e64 s[38:39], s78, v60
	v_subrev_u32_e32 v60, 61, v55
	s_and_b64 s[42:43], s[40:41], s[38:39]
	v_cmp_gt_u32_e64 s[44:45], s79, v60
	v_add_u32_e32 v60, 3, v61
	s_waitcnt lgkmcnt(0)
	v_mfma_f32_16x16x32_bf16 v[56:59], v[64:67], v[44:47], v[56:59]
	v_cndmask_b32_e64 v50, v205, v50, s[42:43]
	v_cmp_gt_u32_e64 s[42:43], s78, v60
	v_subrev_u32_e32 v60, 60, v55
	s_and_b64 s[46:47], s[44:45], s[42:43]
	v_cmp_gt_u32_e64 s[48:49], s79, v60
	v_add_u32_e32 v60, 4, v61
	v_cndmask_b32_e64 v51, v205, v51, s[46:47]
	v_cmp_gt_u32_e64 s[46:47], s78, v60
	s_and_b64 s[50:51], s[48:49], s[46:47]
	v_cndmask_b32_e64 v63, v205, v56, s[50:51]
	v_subrev_u32_e32 v56, 59, v55
	v_cmp_gt_u32_e64 s[52:53], s79, v56
	v_add_u32_e32 v56, 5, v61
	v_cmp_gt_u32_e64 s[50:51], s78, v56
	v_subrev_u32_e32 v56, 58, v55
	s_and_b64 s[54:55], s[52:53], s[50:51]
	v_cmp_gt_u32_e64 s[58:59], s79, v56
	v_add_u32_e32 v56, 6, v61
	v_cndmask_b32_e64 v57, v205, v57, s[54:55]
	v_cmp_gt_u32_e64 s[54:55], s78, v56
	v_subrev_u32_e32 v56, 57, v55
	s_and_b64 s[56:57], s[58:59], s[54:55]
	v_cmp_gt_u32_e64 s[60:61], s79, v56
	v_add_u32_e32 v56, 7, v61
	v_cndmask_b32_e64 v65, v205, v58, s[56:57]
	v_cmp_gt_u32_e64 s[56:57], s78, v56
	s_and_b64 s[64:65], s[60:61], s[56:57]
	v_cndmask_b32_e64 v59, v205, v59, s[64:65]
	v_max_f32_e32 v56, v48, v49
	v_max_f32_e32 v58, v50, v51
	v_max_f32_e32 v60, v65, v59
	v_max3_f32 v60, v63, v57, v60
	v_max3_f32 v56, v56, v58, v60
	v_mov_b32_e32 v58, v56
	s_nop 1
	v_permlane16_swap_b32_e32 v56, v58
	v_max_f32_e32 v56, v56, v58
	v_mov_b32_e32 v58, v56
	s_nop 1
	v_permlane32_swap_b32_e32 v56, v58
	v_max3_f32 v183, v68, v56, v58
	v_sub_f32_e32 v48, v48, v183
	v_exp_f32_e32 v56, v48
	v_sub_f32_e32 v48, v49, v183
	v_exp_f32_e32 v58, v48
	v_sub_f32_e32 v48, v50, v183
	v_exp_f32_e32 v60, v48
	v_sub_f32_e32 v48, v51, v183
	v_exp_f32_e32 v62, v48
	v_sub_f32_e32 v48, v63, v183
	v_exp_f32_e32 v64, v48
	v_sub_f32_e32 v48, v57, v183
	v_exp_f32_e32 v66, v48
	v_sub_f32_e32 v48, v65, v183
	v_sub_f32_e32 v61, v68, v183
	v_exp_f32_e32 v68, v48
	v_sub_f32_e32 v48, v59, v183
	v_exp_f32_e32 v70, v48
	v_exp_f32_e32 v72, v61
	v_add_u32_e32 v57, 0, v78
	ds_read_b64_tr_b16 v[82:83], v57 offset:58144
	ds_read_b64_tr_b16 v[80:81], v57 offset:57600
	ds_read_b64_tr_b16 v[84:85], v57 offset:57632
	v_cvt_pk_bf16_f32 v48, v56, v58
	v_pk_mul_f32 v[30:31], v[30:31], v[72:73] op_sel_hi:[1,0]
	v_pk_mul_f32 v[28:29], v[28:29], v[72:73] op_sel_hi:[1,0]
	v_cvt_pk_bf16_f32 v49, v60, v62
	v_cvt_pk_bf16_f32 v50, v64, v66
	v_cvt_pk_bf16_f32 v51, v68, v70
	ds_read_b64_tr_b16 v[86:87], v57 offset:58176
	v_pk_mul_f32 v[34:35], v[34:35], v[72:73] op_sel_hi:[1,0]
	s_waitcnt lgkmcnt(2)
; __device__ __forceinline__ bf16x8 attn_softmax_step(const f32x4& sA, const f32x4& sB, int cb, int cq, int ncls, int g, float& m, float& lsum, f32x4 (&O)[4]) {
;     float s[8]; bool ok[8];
;     const int c0v = cb + 8 * g, d0 = c0v - cq + 64;
; #pragma unroll
;     for (int j = 0; j < 8; ++j) {
;         ok[j] = ((unsigned)(c0v + j) < (unsigned)ncls) && ((unsigned)(d0 + j) <= 128u);
;         s[j] = ok[j] ? (j < 4 ? sA[j] : sB[j - 4]) : -__builtin_inff(); }
;     float mx = fmaxf(fmaxf(fmaxf(s[0], s[1]), fmaxf(s[2], s[3])), fmaxf(fmaxf(s[4], s[5]), fmaxf(s[6], s[7])));
;     mx = xmax32(xmax16(mx));
;     const float mn = fmaxf(m, mx), alpha = __builtin_amdgcn_exp2f(m - mn);
;     m = mn;
;     float pj[8], ps_ = 0.f;
; #pragma unroll
;     for (int j = 0; j < 8; ++j) { pj[j] = __builtin_amdgcn_exp2f(s[j] - mn); ps_ += pj[j]; }
;     lsum = lsum * alpha + ps_;
; #pragma unroll
;     for (int nbk = 0; nbk < 4; ++nbk) O[nbk] *= alpha;
;     return pack8(pj);
; }
; __device__ __forceinline__ void attn_lds_step(const bf16_t* Kt, const bf16_t* Vt, int rowb, const bf16x8& q0, const bf16x8& q1, int cb, int cq, int ncls,
;                                               int qi, int g, float& m, float& lsum, f32x4 (&O)[4]) {
;     const bf16_t* kA = Kt + (rowb + 8 * (qi >> 2) + (qi & 3)) * 72 + 8 * g;
;     const bf16x8 ka0 = *(const bf16x8*)kA, ka1 = *(const bf16x8*)(kA + 32), kb0 = *(const bf16x8*)(kA + 4 * 72), kb1 = *(const bf16x8*)(kA + 4 * 72 + 32);
;     f32x4 sA = {0.f, 0.f, 0.f, 0.f}, sB = {0.f, 0.f, 0.f, 0.f};
;     sA = MFMA16(ka0, q0, sA); sA = MFMA16(ka1, q1, sA);
;     sB = MFMA16(kb0, q0, sB); sB = MFMA16(kb1, q1, sB);
;     const bf16x8 P = attn_softmax_step(sA, sB, cb, cq, ncls, g, m, lsum, O);
; #pragma unroll
;     for (int nbk = 0; nbk < 4; ++nbk) O[nbk] = MFMA16(gather8(Vt + (rowb + 8 * g) * 68 + 16 * nbk, 68, qi), P, O[nbk]);
; }
; __device__ __forceinline__ void attn_item(const bf16_t* __restrict__ Z, const bf16_t* __restrict__ KA, const bf16_t* __restrict__ VA, bf16_t* __restrict__ MIX, int S, int it) {
;     ...
;     for (int i2 = 0; i2 < 12; ++i2) {
;         attn_lds_step(Kt, Vt, rt[0] + 32 * i2, q0[0], q1[0], P0 + rt[0] - 64 + 32 * i2, P0 + rt[0] + 16 * qi, S, qi, g, m[0], lsum[0], O[0]);
;         attn_lds_step(Kt, Vt, rt[1] + 32 * i2, q0[1], q1[1], P0 + rt[1] - 64 + 32 * i2, P0 + rt[1] + 16 * qi, S, qi, g, m[1], lsum[1], O[1]);
;     }
	v_mfma_f32_16x16x32_bf16 v[28:31], v[80:83], v[48:51], v[28:31]
	ds_read_b64_tr_b16 v[80:81], v57 offset:57664
	ds_read_b64_tr_b16 v[82:83], v57 offset:58208
	v_pk_mul_f32 v[32:33], v[32:33], v[72:73] op_sel_hi:[1,0]
	v_pk_mul_f32 v[26:27], v[26:27], v[72:73] op_sel_hi:[1,0]
	v_pk_mul_f32 v[24:25], v[24:25], v[72:73] op_sel_hi:[1,0]
	s_waitcnt lgkmcnt(0)
	v_mfma_f32_16x16x32_bf16 v[32:35], v[80:83], v[48:51], v[32:35]
	ds_read_b64_tr_b16 v[80:81], v57 offset:57696
	ds_read_b64_tr_b16 v[82:83], v57 offset:58240
	v_pk_mul_f32 v[38:39], v[38:39], v[72:73] op_sel_hi:[1,0]
	v_pk_mul_f32 v[36:37], v[36:37], v[72:73] op_sel_hi:[1,0]
	v_add_u32_e32 v57, 0, v77
	v_mfma_f32_16x16x32_bf16 v[24:27], v[84:87], v[48:51], v[24:27]
	s_and_b64 vcc, s[40:41], vcc
	s_add_i32 s3, s3, 32
	v_add_u32_e32 v77, 0x1200, v77
	s_waitcnt lgkmcnt(0)
	v_mfma_f32_16x16x32_bf16 v[36:39], v[80:83], v[48:51], v[36:39]
	ds_read_b128 v[48:51], v57
	ds_read_b128 v[80:83], v57 offset:64
	ds_read_b128 v[84:87], v57 offset:576
	ds_read_b128 v[88:91], v57 offset:640
	v_subrev_u32_e32 v57, 56, v55
	v_subrev_u32_e32 v55, 55, v55
	s_waitcnt lgkmcnt(3)
	v_mfma_f32_16x16x32_bf16 v[48:51], v[48:51], v[0:3], 0
	v_add_u32_e32 v78, 0x1100, v78
	s_waitcnt lgkmcnt(2)
	v_mfma_f32_16x16x32_bf16 v[48:51], v[80:83], v[4:7], v[48:51]
	s_waitcnt lgkmcnt(1)
	v_mfma_f32_16x16x32_bf16 v[80:83], v[84:87], v[0:3], 0
	s_waitcnt lgkmcnt(0)
	v_mfma_f32_16x16x32_bf16 v[80:83], v[88:91], v[4:7], v[80:83]
	s_nop 3
	v_cndmask_b32_e32 v48, v205, v48, vcc
	s_and_b64 vcc, s[44:45], s[36:37]
	v_cndmask_b32_e32 v49, v205, v49, vcc
	s_and_b64 vcc, s[48:49], s[38:39]
	v_cndmask_b32_e32 v50, v205, v50, vcc
	s_and_b64 vcc, s[52:53], s[42:43]
	v_cndmask_b32_e32 v51, v205, v51, vcc
	s_and_b64 vcc, s[58:59], s[46:47]
	v_cndmask_b32_e32 v65, v205, v80, vcc
	s_and_b64 vcc, s[60:61], s[50:51]
	v_cndmask_b32_e32 v67, v205, v81, vcc
	v_cmp_gt_u32_e32 vcc, s79, v57
	s_and_b64 vcc, vcc, s[54:55]
	v_cndmask_b32_e32 v69, v205, v82, vcc
	v_cmp_gt_u32_e32 vcc, s79, v55
	s_and_b64 vcc, vcc, s[56:57]
	v_cndmask_b32_e32 v55, v205, v83, vcc
	v_max_f32_e32 v57, v48, v49
	v_max_f32_e32 v59, v50, v51
	v_max_f32_e32 v61, v69, v55
	v_max3_f32 v61, v65, v67, v61
	v_max3_f32 v57, v57, v59, v61
	v_mov_b32_e32 v59, v57
	s_nop 1
	v_permlane16_swap_b32_e32 v57, v59
	v_max_f32_e32 v57, v57, v59
	v_mov_b32_e32 v59, v57
	s_nop 1
	v_permlane32_swap_b32_e32 v57, v59
	v_mov_b32_e32 v61, v177
	v_max3_f32 v177, v61, v57, v59
	v_sub_f32_e32 v48, v48, v177
	v_exp_f32_e32 v57, v48
	v_sub_f32_e32 v48, v49, v177
	v_exp_f32_e32 v59, v48
	v_sub_f32_e32 v48, v50, v177
	v_sub_f32_e32 v73, v61, v177
	v_exp_f32_e32 v61, v48
	v_sub_f32_e32 v48, v51, v177
	v_exp_f32_e32 v63, v48
	v_sub_f32_e32 v48, v65, v177
	v_exp_f32_e32 v65, v48
	v_sub_f32_e32 v48, v67, v177
	v_exp_f32_e32 v67, v48
	v_sub_f32_e32 v48, v69, v177
	v_exp_f32_e32 v69, v48
	v_sub_f32_e32 v48, v55, v177
	v_exp_f32_e32 v71, v48
	v_pk_add_f32 v[48:49], v[56:57], 0 op_sel_hi:[1,0]
	v_exp_f32_e32 v73, v73
	v_pk_add_f32 v[48:49], v[58:59], v[48:49]
	v_add_u32_e32 v55, 0, v76
	v_pk_add_f32 v[48:49], v[60:61], v[48:49]
	v_cvt_pk_bf16_f32 v50, v65, v67
	v_pk_add_f32 v[48:49], v[62:63], v[48:49]
	v_cvt_pk_bf16_f32 v51, v69, v71
	v_pk_add_f32 v[48:49], v[64:65], v[48:49]
	v_add_u32_e32 v76, 0x1100, v76
	v_pk_add_f32 v[48:49], v[66:67], v[48:49]
	s_cmpk_eq_i32 s3, 0x180
	v_pk_add_f32 v[48:49], v[68:69], v[48:49]
	s_nop 0
	v_pk_add_f32 v[48:49], v[70:71], v[48:49]
	s_nop 0
	v_pk_fma_f32 v[184:185], v[184:185], v[72:73], v[48:49]
	v_mov_b32_e32 v48, v73
	v_pk_mul_f32 v[18:19], v[18:19], v[48:49] op_sel_hi:[1,0]
	v_pk_mul_f32 v[16:17], v[16:17], v[48:49] op_sel_hi:[1,0]
	v_pk_mul_f32 v[10:11], v[10:11], v[48:49] op_sel_hi:[1,0]
	v_pk_mul_f32 v[8:9], v[8:9], v[48:49] op_sel_hi:[1,0]
	v_pk_mul_f32 v[22:23], v[22:23], v[48:49] op_sel_hi:[1,0]
	v_pk_mul_f32 v[20:21], v[20:21], v[48:49] op_sel_hi:[1,0]
	v_pk_mul_f32 v[14:15], v[14:15], v[48:49] op_sel_hi:[1,0]
	v_pk_mul_f32 v[12:13], v[12:13], v[48:49] op_sel_hi:[1,0]
	v_cvt_pk_bf16_f32 v48, v57, v59
	v_cvt_pk_bf16_f32 v49, v61, v63
	ds_read_b64_tr_b16 v[58:59], v55 offset:58416
	ds_read_b64_tr_b16 v[56:57], v55 offset:57872
	ds_read_b64_tr_b16 v[60:61], v55 offset:57904
	s_waitcnt lgkmcnt(1)
	v_mfma_f32_16x16x32_bf16 v[16:19], v[56:59], v[48:51], v[16:19]
	ds_read_b64_tr_b16 v[62:63], v55 offset:58448
	ds_read_b64_tr_b16 v[56:57], v55 offset:57936
	ds_read_b64_tr_b16 v[58:59], v55 offset:58480
	s_waitcnt lgkmcnt(0)
	v_mfma_f32_16x16x32_bf16 v[20:23], v[56:59], v[48:51], v[20:23]
	ds_read_b64_tr_b16 v[56:57], v55 offset:57968
	ds_read_b64_tr_b16 v[58:59], v55 offset:58512
	v_mfma_f32_16x16x32_bf16 v[8:11], v[60:63], v[48:51], v[8:11]
	s_waitcnt lgkmcnt(0)
	v_mfma_f32_16x16x32_bf16 v[12:15], v[56:59], v[48:51], v[12:15]
	s_cbranch_scc0 .LBB0_403
; template <int NROWS>
; __device__ __forceinline__ void attn_stage(const bf16_t* __restrict__ ka, const bf16_t* __restrict__ va, bf16_t* Kt, bf16_t* Vt, int c0, int ncls, int rd, int dsh, int tid) {
;     ...
;     for (int u = 0; u < IT; ++u) { const int idx = min(tid + u * NTHR, NROWS * 16 - 1);
;         const int i = idx >> 4, ch = idx & 15, isv = ch >> 3, c8 = ch & 7; const int c = min(max(c0 + i, 0), ncls - 1);
;         v[u] = *(const u32x4*)((isv ? va : ka) + (size_t)(rd + (c << dsh)) * 64 + 8 * c8); }
; __device__ __forceinline__ void attn_item(const bf16_t* __restrict__ Z, const bf16_t* __restrict__ KA, const bf16_t* __restrict__ VA, bf16_t* __restrict__ MIX, int S, int it) {
;     ...
;     for (int rho = 0; rho < 2; ++rho) {
;         __syncthreads();
;         attn_stage<200>(ka, va, Kt, Vt, (P0 >> 2) - 64, S >> 2, 2 * rho, 2, tid);
;         attn_stage<200>(ka, va, Kt + 200 * 72, Vt + 200 * 68, (P0 >> 2) - 64, S >> 2, 2 * rho + 1, 2, tid);
;         __syncthreads();
;         const int r = rt[rho], cls = (r & 3) - 2 * rho, c0 = (P0 >> 2) + (r >> 2);
	s_lshl_b32 s18, s2, 6
	v_min_i32_e32 v50, 0xc7f, v187
	s_sub_i32 s2, s18, 64
	v_ashrrev_i32_e32 v59, 4, v50
	v_add_u32_e32 v48, s2, v59
	v_max_i32_e32 v48, 0, v48
	v_readlane_b32 s3, v255, 38
	v_mov_b32_e32 v63, s95
	v_mov_b32_e32 v67, s7
	v_min_u32_e32 v51, s3, v48
	v_and_b32_e32 v48, 8, v50
	v_cmp_eq_u32_e32 vcc, 0, v48
	v_mov_b32_e32 v71, s94
	v_mov_b32_e32 v75, s6
	v_lshlrev_b32_e32 v50, 4, v50
	v_cndmask_b32_e32 v49, v63, v67, vcc
	v_cndmask_b32_e32 v48, v71, v75, vcc
	v_and_b32_e32 v178, 0x70, v50
	v_lshl_add_u64 v[56:57], v[48:49], 0, v[178:179]
	v_min_i32_e32 v48, 0xa7f, v187
	v_add_u32_e32 v49, 0x200, v48
	v_ashrrev_i32_e32 v79, 4, v49
	v_add_u32_e32 v49, s2, v79
	v_max_i32_e32 v49, 0, v49
	v_and_b32_e32 v50, 8, v48
	v_min_u32_e32 v49, s3, v49
	v_cmp_eq_u32_e64 s[36:37], 0, v50
	v_lshlrev_b32_e32 v48, 4, v48
	v_lshlrev_b32_e32 v58, 2, v51
	v_cndmask_b32_e64 v51, v63, v67, s[36:37]
	v_cndmask_b32_e64 v50, v71, v75, s[36:37]
	v_lshlrev_b32_e32 v62, 2, v49
	v_and_b32_e32 v48, 0x70, v48
	v_mov_b32_e32 v49, v179
	v_lshl_add_u64 v[60:61], v[50:51], 0, v[48:49]
	v_min_i32_e32 v49, 0x87f, v187
	v_add_u32_e32 v50, 0x400, v49
	v_ashrrev_i32_e32 v83, 4, v50
	v_add_u32_e32 v50, s2, v83
	v_max_i32_e32 v50, 0, v50
	v_and_b32_e32 v51, 8, v49
	v_min_u32_e32 v50, s3, v50
	v_cmp_eq_u32_e64 s[38:39], 0, v51
	v_lshlrev_b32_e32 v49, 4, v49
	v_lshlrev_b32_e32 v66, 2, v50
	v_cndmask_b32_e64 v55, v63, v67, s[38:39]
	v_cndmask_b32_e64 v54, v71, v75, s[38:39]
	v_and_b32_e32 v50, 0x70, v49
	v_mov_b32_e32 v51, v179
	v_min_i32_e32 v49, 0x67f, v187
	v_lshl_add_u64 v[64:65], v[54:55], 0, v[50:51]
	v_add_u32_e32 v51, 0x600, v49
	v_ashrrev_i32_e32 v90, 4, v51
	v_add_u32_e32 v51, s2, v90
	v_max_i32_e32 v51, 0, v51
	v_and_b32_e32 v54, 8, v49
	v_lshlrev_b32_e32 v49, 4, v49
	v_min_u32_e32 v51, s3, v51
	v_cmp_eq_u32_e64 s[40:41], 0, v54
	v_and_b32_e32 v54, 0x70, v49
	v_min_i32_e32 v49, 0x47f, v187
	v_lshlrev_b32_e32 v70, 2, v51
	v_add_u32_e32 v51, 0x800, v49
	v_ashrrev_i32_e32 v91, 4, v51
	v_cndmask_b32_e64 v69, v63, v67, s[40:41]
	v_cndmask_b32_e64 v68, v71, v75, s[40:41]
	v_mov_b32_e32 v55, v179
	v_add_u32_e32 v51, s2, v91
	v_lshl_add_u64 v[68:69], v[68:69], 0, v[54:55]
	v_max_i32_e32 v51, 0, v51
	v_and_b32_e32 v55, 8, v49
	v_lshlrev_b32_e32 v49, 4, v49
	v_min_u32_e32 v51, s3, v51
	v_and_b32_e32 v84, 0x70, v49
	v_min_i32_e32 v49, 0x27f, v187
	v_lshlrev_b32_e32 v74, 2, v51
	v_add_u32_e32 v51, 0xa00, v49
	v_ashrrev_i32_e32 v92, 4, v51
	v_add_u32_e32 v51, s2, v92
	v_cmp_eq_u32_e64 s[42:43], 0, v55
	v_max_i32_e32 v51, 0, v51
	v_and_b32_e32 v55, 8, v49
	v_lshlrev_b32_e32 v49, 4, v49
	v_min_u32_e32 v51, s3, v51
	v_and_b32_e32 v86, 0x70, v49
	v_min_i32_e32 v49, 0x7f, v187
	v_lshlrev_b32_e32 v78, 2, v51
	v_add_u32_e32 v51, 0xc00, v49
	v_ashrrev_i32_e32 v93, 4, v51
	v_cmp_eq_u32_e64 s[44:45], 0, v55
	v_add_u32_e32 v51, s2, v93
	v_and_b32_e32 v55, 8, v49
	v_lshlrev_b32_e32 v49, 4, v49
	v_max_i32_e32 v51, 0, v51
	v_cmp_eq_u32_e64 s[46:47], 0, v55
	v_and_b32_e32 v88, 0x70, v49
	v_cndmask_b32_e32 v49, v206, v207, vcc
	v_readlane_b32 s2, v255, 0
	v_cndmask_b32_e64 v72, v71, v75, s[42:43]
	v_cndmask_b32_e64 v76, v71, v75, s[44:45]
	v_min_u32_e32 v51, s3, v51
	v_cndmask_b32_e64 v80, v71, v75, s[46:47]
	v_mov_b32_e32 v71, s2
	v_mul_lo_u32 v49, v49, v59
	v_cndmask_b32_e64 v73, v63, v67, s[42:43]
	v_mov_b32_e32 v85, v179
	v_lshlrev_b32_e32 v82, 2, v51
	v_cndmask_b32_e64 v51, v71, 0, vcc
	v_lshlrev_b32_e32 v49, 1, v49
	v_lshl_add_u64 v[72:73], v[72:73], 0, v[84:85]
	v_add3_u32 v85, v51, v49, v178
	v_cndmask_b32_e64 v51, v206, v207, s[36:37]
	v_mul_lo_u32 v51, v51, v79
	v_cndmask_b32_e64 v77, v63, v67, s[44:45]
	v_mov_b32_e32 v87, v179
	v_cndmask_b32_e64 v55, v71, 0, s[36:37]
	v_lshlrev_b32_e32 v51, 1, v51
	v_lshl_add_u64 v[76:77], v[76:77], 0, v[86:87]
	v_add3_u32 v87, v55, v51, v48
	v_cndmask_b32_e64 v55, v206, v207, s[38:39]
	v_mul_lo_u32 v55, v55, v83
	v_cndmask_b32_e64 v81, v63, v67, s[46:47]
	v_mov_b32_e32 v89, v179
	v_cndmask_b32_e64 v59, v71, 0, s[38:39]
	v_lshlrev_b32_e32 v55, 1, v55
	v_lshl_add_u64 v[80:81], v[80:81], 0, v[88:89]
	v_add3_u32 v89, v59, v55, v50
	v_cndmask_b32_e64 v59, v206, v207, s[40:41]
	v_mul_lo_u32 v59, v59, v90
	v_cndmask_b32_e64 v63, v71, 0, s[40:41]
	v_lshlrev_b32_e32 v59, 1, v59
	v_add3_u32 v90, v63, v59, v54
	v_cndmask_b32_e64 v63, v206, v207, s[42:43]
	v_mul_lo_u32 v63, v63, v91
	v_cndmask_b32_e64 v67, v71, 0, s[42:43]
	v_lshlrev_b32_e32 v63, 1, v63
	v_add3_u32 v91, v67, v63, v84
	v_cndmask_b32_e64 v67, v206, v207, s[44:45]
	s_mov_b64 s[2:3], src_shared_base
	s_cmp_lg_u32 0, -1
	v_mul_lo_u32 v67, v67, v92
	s_cselect_b32 s2, 0, 0
	v_cndmask_b32_e64 v75, v71, 0, s[44:45]
	v_lshlrev_b32_e32 v67, 1, v67
	s_cselect_b32 s3, s3, 0
	s_add_u32 s2, s2, 0x7080
	v_add3_u32 v92, v75, v67, v86
	v_cndmask_b32_e64 v75, v206, v207, s[46:47]
	s_addc_u32 s3, s3, 0
	v_cndmask_b32_e64 v79, v71, 0, s[46:47]
	v_mul_lo_u32 v71, v75, v93
	s_cmp_lg_u64 s[2:3], 0
	v_lshlrev_b32_e32 v71, 1, v71
	s_cselect_b32 s2, s2, -1
	s_add_i32 s3, 0, 0x14b40
	v_add3_u32 v93, v79, v71, v88
	v_mov_b32_e32 v75, s3
	v_mov_b32_e32 v79, s2
	v_cndmask_b32_e32 v83, v75, v79, vcc
	v_add3_u32 v97, v83, v49, v178
	v_cndmask_b32_e64 v49, v75, v79, s[36:37]
	v_add3_u32 v98, v49, v51, v48
	v_cndmask_b32_e64 v48, v75, v79, s[38:39]
	v_add3_u32 v99, v48, v55, v50
	v_cndmask_b32_e64 v48, v75, v79, s[40:41]
	v_add3_u32 v100, v48, v59, v54
	v_cndmask_b32_e64 v48, v75, v79, s[42:43]
	v_add3_u32 v84, v48, v63, v84
	v_mov_b32_e32 v63, v179
	v_cndmask_b32_e64 v48, v75, v79, s[44:45]
	v_lshlrev_b64 v[54:55], 7, v[62:63]
	v_add3_u32 v86, v48, v67, v86
	v_lshl_add_u64 v[54:55], v[60:61], 0, v[54:55]
	v_mov_b32_e32 v67, v179
	v_cndmask_b32_e64 v48, v75, v79, s[46:47]
	s_barrier
; template <int NROWS>
; __device__ __forceinline__ void attn_stage(const bf16_t* __restrict__ ka, const bf16_t* __restrict__ va, bf16_t* Kt, bf16_t* Vt, int c0, int ncls, int rd, int dsh, int tid) {
;     ...
;     for (int u = 0; u < IT; ++u) { const int idx = min(tid + u * NTHR, NROWS * 16 - 1);
;         const int i = idx >> 4, ch = idx & 15, isv = ch >> 3, c8 = ch & 7; const int c = min(max(c0 + i, 0), ncls - 1);
;         v[u] = *(const u32x4*)((isv ? va : ka) + (size_t)(rd + (c << dsh)) * 64 + 8 * c8); }
; #pragma unroll
;     for (int u = 0; u < IT; ++u) { const int idx = min(tid + u * NTHR, NROWS * 16 - 1);
;         const int i = idx >> 4, ch = idx & 15, isv = ch >> 3, c8 = ch & 7;
;         bf16_t* d = isv ? (Vt + i * 68 + 8 * c8) : (Kt + i * 72 + 8 * c8);
;         *(u32x2*)d = (u32x2){v[u].x, v[u].y}; *(u32x2*)(d + 4) = (u32x2){v[u].z, v[u].w}; }
; __device__ __forceinline__ void attn_item(const bf16_t* __restrict__ Z, const bf16_t* __restrict__ KA, const bf16_t* __restrict__ VA, bf16_t* __restrict__ MIX, int S, int it) {
;     ...
;         const int r = rt[rho], cls = (r & 3) - 2 * rho, c0 = (P0 >> 2) + (r >> 2);
; #pragma unroll 2
;         for (int i2 = 0; i2 < 6; ++i2)
;             attn_lds_step(Kt + cls * 200 * 72, Vt + cls * 200 * 68, (r >> 2) + 32 * i2, q0[rho], q1[rho], c0 - 64 + 32 * i2, c0 + 4 * qi, S >> 2, qi, g, m[rho], lsum[rho], O[rho]);
	global_load_dwordx4 v[102:105], v[54:55], off
	v_lshlrev_b64 v[54:55], 7, v[66:67]
	v_add3_u32 v88, v48, v71, v88
	v_mov_b32_e32 v59, v179
	v_lshl_add_u64 v[54:55], v[64:65], 0, v[54:55]
	v_mov_b32_e32 v71, v179
	v_lshlrev_b64 v[48:49], 7, v[58:59]
	global_load_dwordx4 v[106:109], v[54:55], off
	v_lshlrev_b64 v[54:55], 7, v[70:71]
	v_lshl_add_u64 v[48:49], v[56:57], 0, v[48:49]
	v_lshl_add_u64 v[54:55], v[68:69], 0, v[54:55]
	v_mov_b32_e32 v75, v179
	global_load_dwordx4 v[48:51], v[48:49], off
	v_mov_b32_e32 v79, v179
	global_load_dwordx4 v[110:113], v[54:55], off
	v_lshlrev_b64 v[54:55], 7, v[74:75]
	v_lshl_add_u64 v[54:55], v[72:73], 0, v[54:55]
	global_load_dwordx4 v[114:117], v[54:55], off
	v_lshlrev_b64 v[54:55], 7, v[78:79]
	v_lshl_add_u64 v[54:55], v[76:77], 0, v[54:55]
	v_mov_b32_e32 v83, v179
	global_load_dwordx4 v[118:121], v[54:55], off
	v_lshlrev_b64 v[54:55], 7, v[82:83]
	v_lshl_add_u64 v[54:55], v[80:81], 0, v[54:55]
	global_load_dwordx4 v[122:125], v[54:55], off
	v_or_b32_e32 v178, 1, v58
	s_waitcnt vmcnt(4)
	ds_write2_b64 v85, v[48:49], v[50:51] offset1:1
	ds_write2_b64 v87, v[102:103], v[104:105] offset1:1
	ds_write2_b64 v89, v[106:107], v[108:109] offset1:1
	s_waitcnt vmcnt(3)
	ds_write2_b64 v90, v[110:111], v[112:113] offset1:1
	s_waitcnt vmcnt(2)
	ds_write2_b64 v91, v[114:115], v[116:117] offset1:1
	s_waitcnt vmcnt(1)
	ds_write2_b64 v92, v[118:119], v[120:121] offset1:1
	s_waitcnt vmcnt(0)
	ds_write2_b64 v93, v[122:123], v[124:125] offset1:1
	v_lshlrev_b64 v[48:49], 7, v[178:179]
	v_or_b32_e32 v178, 1, v62
	v_lshlrev_b64 v[54:55], 7, v[178:179]
	v_lshl_add_u64 v[54:55], v[60:61], 0, v[54:55]
	v_or_b32_e32 v178, 1, v66
	global_load_dwordx4 v[102:105], v[54:55], off
	v_lshlrev_b64 v[54:55], 7, v[178:179]
	v_lshl_add_u64 v[54:55], v[64:65], 0, v[54:55]
	v_or_b32_e32 v178, 1, v70
	global_load_dwordx4 v[106:109], v[54:55], off
	v_lshlrev_b64 v[54:55], 7, v[178:179]
	v_lshl_add_u64 v[48:49], v[56:57], 0, v[48:49]
	v_lshl_add_u64 v[54:55], v[68:69], 0, v[54:55]
	v_or_b32_e32 v178, 1, v74
	global_load_dwordx4 v[48:51], v[48:49], off
	v_mul_u32_u24_e32 v101, 0x88, v214
	global_load_dwordx4 v[110:113], v[54:55], off
	v_lshlrev_b64 v[54:55], 7, v[178:179]
	v_lshl_add_u64 v[54:55], v[72:73], 0, v[54:55]
	v_or_b32_e32 v178, 1, v78
	global_load_dwordx4 v[114:117], v[54:55], off
	v_lshlrev_b64 v[54:55], 7, v[178:179]
	v_lshl_add_u64 v[54:55], v[76:77], 0, v[54:55]
	v_or_b32_e32 v178, 1, v82
	global_load_dwordx4 v[118:121], v[54:55], off
	v_lshlrev_b64 v[54:55], 7, v[178:179]
	v_lshl_add_u64 v[54:55], v[80:81], 0, v[54:55]
	global_load_dwordx4 v[122:125], v[54:55], off
	s_waitcnt vmcnt(4)
	ds_write2_b64 v97, v[48:49], v[50:51] offset1:1
	ds_write2_b64 v98, v[102:103], v[104:105] offset1:1
	ds_write2_b64 v99, v[106:107], v[108:109] offset1:1
	s_waitcnt vmcnt(3)
	ds_write2_b64 v100, v[110:111], v[112:113] offset1:1
	s_waitcnt vmcnt(2)
	ds_write2_b64 v84, v[114:115], v[116:117] offset1:1
	s_waitcnt vmcnt(1)
	ds_write2_b64 v86, v[118:119], v[120:121] offset1:1
	s_waitcnt vmcnt(0)
	ds_write2_b64 v88, v[122:123], v[124:125] offset1:1
	v_ashrrev_i32_e32 v48, 7, v187
	v_mul_u32_u24_e32 v50, 0x6a40, v211
	s_movk_i32 s2, 0x88
	v_add3_u32 v50, v50, v101, v94
	v_mul_lo_u32 v51, v48, s2
	v_add3_u32 v59, v50, v51, v96
	v_add_u32_e32 v50, v48, v212
	s_movk_i32 s3, 0x90
	v_mul_u32_u24_e32 v49, 0x7080, v211
	v_mul_lo_u32 v51, v50, s3
	v_add3_u32 v67, v48, s18, v186
	v_add_u32_e32 v48, v50, v53
	v_add3_u32 v51, v49, v95, v51
	s_movk_i32 s2, 0x1200
	v_mul_lo_u32 v48, v48, s3
	v_add3_u32 v63, v51, v52, s2
	v_add3_u32 v75, v49, v48, v52
	s_mov_b32 s15, 0
	v_sub_u32_e32 v71, v186, v213
	v_mov_b32_e32 v79, v75
	v_mov_b32_e32 v83, v63
	v_mov_b32_e32 v94, v59
	s_waitcnt lgkmcnt(0)
	s_barrier
.LBB0_405:
	v_add_u32_e32 v95, 0, v79
	ds_read_b128 v[48:51], v95
	ds_read_b128 v[52:55], v95 offset:64
	ds_read_b128 v[102:105], v95 offset:576
	ds_read_b128 v[106:109], v95 offset:640
	v_add_u32_e32 v95, s15, v67
	s_waitcnt lgkmcnt(3)
	v_mfma_f32_16x16x32_bf16 v[48:51], v[48:51], v[40:43], 0
	v_subrev_u32_e32 v101, 64, v95
	v_add_u32_e32 v96, s15, v71
	v_cmp_gt_u32_e32 vcc, s62, v101
	s_waitcnt lgkmcnt(2)
	v_mfma_f32_16x16x32_bf16 v[48:51], v[52:55], v[44:47], v[48:51]
	v_cmp_gt_u32_e64 s[36:37], s78, v96
	s_and_b64 vcc, vcc, s[36:37]
	v_subrev_u32_e32 v101, 63, v95
	s_waitcnt lgkmcnt(1)
	v_mfma_f32_16x16x32_bf16 v[52:55], v[102:105], v[40:43], 0
	s_add_i32 s15, s15, 64
	s_nop 1
	v_cndmask_b32_e32 v48, v205, v48, vcc
	v_cmp_gt_u32_e32 vcc, s62, v101
	v_add_u32_e32 v101, 1, v96
	v_cmp_gt_u32_e64 s[36:37], s78, v101
	s_and_b64 vcc, vcc, s[36:37]
	v_subrev_u32_e32 v101, 62, v95
	v_cndmask_b32_e32 v49, v205, v49, vcc
	v_cmp_gt_u32_e32 vcc, s62, v101
	v_add_u32_e32 v101, 2, v96
	v_cmp_gt_u32_e64 s[36:37], s78, v101
	s_and_b64 vcc, vcc, s[36:37]
	v_subrev_u32_e32 v101, 61, v95
	v_cndmask_b32_e32 v50, v205, v50, vcc
	v_cmp_gt_u32_e32 vcc, s62, v101
	v_add_u32_e32 v101, 3, v96
	v_cmp_gt_u32_e64 s[36:37], s78, v101
	s_waitcnt lgkmcnt(0)
; __device__ __forceinline__ float xmax16(float m) { auto rr = __builtin_amdgcn_permlane16_swap(__float_as_uint(m), __float_as_uint(m), false, false); return fmaxf(__uint_as_float(rr[0]), __uint_as_float(rr[1])); }
; __device__ __forceinline__ float xmax32(float m) { auto rr = __builtin_amdgcn_permlane32_swap(__float_as_uint(m), __float_as_uint(m), false, false); return fmaxf(__uint_as_float(rr[0]), __uint_as_float(rr[1])); }
; #define MFMA16(a, b, c) __builtin_amdgcn_mfma_f32_16x16x32_bf16((a), (b), (c), 0, 0, 0)
; __device__ __forceinline__ bf16x8 attn_softmax_step(const f32x4& sA, const f32x4& sB, int cb, int cq, int ncls, int g, float& m, float& lsum, f32x4 (&O)[4]) {
;     float s[8]; bool ok[8];
;     const int c0v = cb + 8 * g, d0 = c0v - cq + 64;
; #pragma unroll
;     for (int j = 0; j < 8; ++j) {
;         ok[j] = ((unsigned)(c0v + j) < (unsigned)ncls) && ((unsigned)(d0 + j) <= 128u);
;         s[j] = ok[j] ? (j < 4 ? sA[j] : sB[j - 4]) : -__builtin_inff(); }
;     float mx = fmaxf(fmaxf(fmaxf(s[0], s[1]), fmaxf(s[2], s[3])), fmaxf(fmaxf(s[4], s[5]), fmaxf(s[6], s[7])));
;     mx = xmax32(xmax16(mx));
;     const float mn = fmaxf(m, mx), alpha = __builtin_amdgcn_exp2f(m - mn);
;     m = mn;
;     float pj[8], ps_ = 0.f;
; #pragma unroll
;     for (int j = 0; j < 8; ++j) { pj[j] = __builtin_amdgcn_exp2f(s[j] - mn); ps_ += pj[j]; }
;     lsum = lsum * alpha + ps_;
; #pragma unroll
;     for (int nbk = 0; nbk < 4; ++nbk) O[nbk] *= alpha;
;     return pack8(pj);
; }
; __device__ __forceinline__ void attn_lds_step(const bf16_t* Kt, const bf16_t* Vt, int rowb, const bf16x8& q0, const bf16x8& q1, int cb, int cq, int ncls,
;                                               int qi, int g, float& m, float& lsum, f32x4 (&O)[4]) {
;     const bf16_t* kA = Kt + (rowb + 8 * (qi >> 2) + (qi & 3)) * 72 + 8 * g;
;     const bf16x8 ka0 = *(const bf16x8*)kA, ka1 = *(const bf16x8*)(kA + 32), kb0 = *(const bf16x8*)(kA + 4 * 72), kb1 = *(const bf16x8*)(kA + 4 * 72 + 32);
;     f32x4 sA = {0.f, 0.f, 0.f, 0.f}, sB = {0.f, 0.f, 0.f, 0.f};
;     sA = MFMA16(ka0, q0, sA); sA = MFMA16(ka1, q1, sA);
;     sB = MFMA16(kb0, q0, sB); sB = MFMA16(kb1, q1, sB);
;     const bf16x8 P = attn_softmax_step(sA, sB, cb, cq, ncls, g, m, lsum, O);
; #pragma unroll
;     for (int nbk = 0; nbk < 4; ++nbk) O[nbk] = MFMA16(gather8(Vt + (rowb + 8 * g) * 68 + 16 * nbk, 68, qi), P, O[nbk]);
; }
	v_mfma_f32_16x16x32_bf16 v[52:55], v[106:109], v[44:47], v[52:55]
	s_and_b64 vcc, vcc, s[36:37]
	v_subrev_u32_e32 v101, 60, v95
	v_cndmask_b32_e32 v51, v205, v51, vcc
	v_cmp_gt_u32_e32 vcc, s62, v101
	v_add_u32_e32 v101, 4, v96
	v_cmp_gt_u32_e64 s[36:37], s78, v101
	s_and_b64 vcc, vcc, s[36:37]
	v_subrev_u32_e32 v101, 59, v95
	v_cndmask_b32_e32 v52, v205, v52, vcc
	v_cmp_gt_u32_e32 vcc, s62, v101
	v_add_u32_e32 v101, 5, v96
	v_cmp_gt_u32_e64 s[36:37], s78, v101
	s_and_b64 vcc, vcc, s[36:37]
	v_subrev_u32_e32 v101, 58, v95
	v_cndmask_b32_e32 v53, v205, v53, vcc
	v_cmp_gt_u32_e32 vcc, s62, v101
	v_add_u32_e32 v101, 6, v96
	v_cmp_gt_u32_e64 s[36:37], s78, v101
	s_and_b64 vcc, vcc, s[36:37]
	v_subrev_u32_e32 v101, 57, v95
	v_cndmask_b32_e32 v54, v205, v54, vcc
	v_cmp_gt_u32_e32 vcc, s62, v101
	v_add_u32_e32 v101, 7, v96
	v_cmp_gt_u32_e64 s[36:37], s78, v101
	s_and_b64 vcc, vcc, s[36:37]
	v_cndmask_b32_e32 v55, v205, v55, vcc
	v_max_f32_e32 v101, v48, v49
	v_max_f32_e32 v102, v50, v51
	v_max_f32_e32 v103, v54, v55
	v_max3_f32 v103, v52, v53, v103
	v_max3_f32 v101, v101, v102, v103
	v_mov_b32_e32 v102, v101
	s_nop 1
	v_permlane16_swap_b32_e32 v101, v102
	v_max_f32_e32 v101, v101, v102
	v_mov_b32_e32 v102, v101
	s_nop 1
	v_permlane32_swap_b32_e32 v101, v102
	v_max3_f32 v102, v183, v101, v102
	v_sub_f32_e32 v48, v48, v102
	v_exp_f32_e32 v105, v48
	v_sub_f32_e32 v49, v49, v102
	v_exp_f32_e32 v106, v49
	v_sub_f32_e32 v49, v50, v102
	v_exp_f32_e32 v107, v49
	v_sub_f32_e32 v49, v51, v102
	v_exp_f32_e32 v108, v49
	v_sub_f32_e32 v49, v52, v102
	v_add_f32_e32 v48, 0, v105
	v_exp_f32_e32 v109, v49
	v_sub_f32_e32 v49, v53, v102
	v_add_f32_e32 v48, v106, v48
	v_exp_f32_e32 v110, v49
	v_sub_f32_e32 v49, v54, v102
	v_sub_f32_e32 v103, v183, v102
	v_add_f32_e32 v48, v107, v48
	v_exp_f32_e32 v111, v49
	v_sub_f32_e32 v49, v55, v102
	v_add_f32_e32 v48, v108, v48
	v_exp_f32_e32 v112, v49
	v_exp_f32_e32 v104, v103
	v_add_f32_e32 v48, v109, v48
	v_add_f32_e32 v48, v110, v48
	v_add_f32_e32 v48, v111, v48
	v_add_f32_e32 v101, v112, v48
	v_pk_mul_f32 v[54:55], v[30:31], v[104:105] op_sel_hi:[1,0]
	v_pk_mul_f32 v[30:31], v[34:35], v[104:105] op_sel_hi:[1,0]
	v_cvt_pk_bf16_f32 v35, v111, v112
	v_add_u32_e32 v112, 0, v94
	v_fmac_f32_e32 v101, v184, v104
	v_pk_mul_f32 v[52:53], v[28:29], v[104:105] op_sel_hi:[1,0]
	v_pk_mul_f32 v[50:51], v[26:27], v[104:105] op_sel_hi:[1,0]
	v_pk_mul_f32 v[48:49], v[24:25], v[104:105] op_sel_hi:[1,0]
	v_pk_mul_f32 v[28:29], v[32:33], v[104:105] op_sel_hi:[1,0]
	v_pk_mul_f32 v[26:27], v[38:39], v[104:105] op_sel_hi:[1,0]
	v_pk_mul_f32 v[24:25], v[36:37], v[104:105] op_sel_hi:[1,0]
	v_cvt_pk_bf16_f32 v32, v105, v106
	ds_read_b64_tr_b16 v[38:39], v112 offset:58144
	ds_read_b64_tr_b16 v[36:37], v112 offset:57600
	ds_read_b64_tr_b16 v[104:105], v112 offset:57632
	v_cvt_pk_bf16_f32 v33, v107, v108
	v_cvt_pk_bf16_f32 v34, v109, v110
	ds_read_b64_tr_b16 v[106:107], v112 offset:58176
	v_add_u32_e32 v103, 0, v83
	s_waitcnt lgkmcnt(2)
	v_mfma_f32_16x16x32_bf16 v[36:39], v[36:39], v[32:35], v[52:55]
	s_nop 2
	ds_read_b64_tr_b16 v[52:53], v112 offset:57664
	ds_read_b64_tr_b16 v[54:55], v112 offset:58208
	v_add_u32_e32 v94, 0x2200, v94
	v_add_u32_e32 v83, 0x2400, v83
	s_waitcnt lgkmcnt(0)
	v_mfma_f32_16x16x32_bf16 v[28:31], v[52:55], v[32:35], v[28:31]
	ds_read_b64_tr_b16 v[52:53], v112 offset:57696
	ds_read_b64_tr_b16 v[54:55], v112 offset:58240
	v_add_u32_e32 v79, 0x2400, v79
	v_mfma_f32_16x16x32_bf16 v[48:51], v[104:107], v[32:35], v[48:51]
	s_waitcnt lgkmcnt(0)
	v_mfma_f32_16x16x32_bf16 v[24:27], v[52:55], v[32:35], v[24:27]
	ds_read_b128 v[32:35], v103
	ds_read_b128 v[52:55], v103 offset:64
	ds_read_b128 v[104:107], v103 offset:576
	ds_read_b128 v[108:111], v103 offset:640
	v_subrev_u32_e32 v103, 32, v95
	v_cmp_gt_u32_e32 vcc, s62, v103
	s_waitcnt lgkmcnt(3)
	v_mfma_f32_16x16x32_bf16 v[32:35], v[32:35], v[40:43], 0
	v_subrev_u32_e32 v103, 31, v95
	s_waitcnt lgkmcnt(2)
	v_mfma_f32_16x16x32_bf16 v[32:35], v[52:55], v[44:47], v[32:35]
	s_waitcnt lgkmcnt(1)
	v_mfma_f32_16x16x32_bf16 v[52:55], v[104:107], v[40:43], 0
	v_add_u32_e32 v104, 32, v96
	v_cmp_gt_u32_e64 s[36:37], s78, v104
	s_and_b64 vcc, vcc, s[36:37]
	s_nop 2
	v_cndmask_b32_e32 v32, v205, v32, vcc
	v_cmp_gt_u32_e32 vcc, s62, v103
	v_add_u32_e32 v103, 33, v96
	v_cmp_gt_u32_e64 s[36:37], s78, v103
	s_and_b64 vcc, vcc, s[36:37]
	v_subrev_u32_e32 v103, 30, v95
	v_cndmask_b32_e32 v33, v205, v33, vcc
	v_cmp_gt_u32_e32 vcc, s62, v103
	v_add_u32_e32 v103, 34, v96
	v_cmp_gt_u32_e64 s[36:37], s78, v103
	s_and_b64 vcc, vcc, s[36:37]
	v_subrev_u32_e32 v103, 29, v95
	v_cndmask_b32_e32 v34, v205, v34, vcc
	v_cmp_gt_u32_e32 vcc, s62, v103
	v_add_u32_e32 v103, 35, v96
	v_cmp_gt_u32_e64 s[36:37], s78, v103
	s_waitcnt lgkmcnt(0)
; __device__ __forceinline__ bf16x8 attn_softmax_step(const f32x4& sA, const f32x4& sB, int cb, int cq, int ncls, int g, float& m, float& lsum, f32x4 (&O)[4]) {
;     float s[8]; bool ok[8];
;     const int c0v = cb + 8 * g, d0 = c0v - cq + 64;
; #pragma unroll
;     for (int j = 0; j < 8; ++j) {
;         ok[j] = ((unsigned)(c0v + j) < (unsigned)ncls) && ((unsigned)(d0 + j) <= 128u);
;         s[j] = ok[j] ? (j < 4 ? sA[j] : sB[j - 4]) : -__builtin_inff(); }
;     float mx = fmaxf(fmaxf(fmaxf(s[0], s[1]), fmaxf(s[2], s[3])), fmaxf(fmaxf(s[4], s[5]), fmaxf(s[6], s[7])));
;     mx = xmax32(xmax16(mx));
;     const float mn = fmaxf(m, mx), alpha = __builtin_amdgcn_exp2f(m - mn);
;     m = mn;
;     float pj[8], ps_ = 0.f;
; #pragma unroll
;     for (int j = 0; j < 8; ++j) { pj[j] = __builtin_amdgcn_exp2f(s[j] - mn); ps_ += pj[j]; }
;     lsum = lsum * alpha + ps_;
; #pragma unroll
;     for (int nbk = 0; nbk < 4; ++nbk) O[nbk] *= alpha;
;     return pack8(pj);
; }
; __device__ __forceinline__ void attn_lds_step(const bf16_t* Kt, const bf16_t* Vt, int rowb, const bf16x8& q0, const bf16x8& q1, int cb, int cq, int ncls,
;                                               int qi, int g, float& m, float& lsum, f32x4 (&O)[4]) {
;     const bf16_t* kA = Kt + (rowb + 8 * (qi >> 2) + (qi & 3)) * 72 + 8 * g;
;     const bf16x8 ka0 = *(const bf16x8*)kA, ka1 = *(const bf16x8*)(kA + 32), kb0 = *(const bf16x8*)(kA + 4 * 72), kb1 = *(const bf16x8*)(kA + 4 * 72 + 32);
;     f32x4 sA = {0.f, 0.f, 0.f, 0.f}, sB = {0.f, 0.f, 0.f, 0.f};
;     sA = MFMA16(ka0, q0, sA); sA = MFMA16(ka1, q1, sA);
;     sB = MFMA16(kb0, q0, sB); sB = MFMA16(kb1, q1, sB);
;     const bf16x8 P = attn_softmax_step(sA, sB, cb, cq, ncls, g, m, lsum, O);
; #pragma unroll
;     for (int nbk = 0; nbk < 4; ++nbk) O[nbk] = MFMA16(gather8(Vt + (rowb + 8 * g) * 68 + 16 * nbk, 68, qi), P, O[nbk]);
; }
; __device__ __forceinline__ void attn_item(const bf16_t* __restrict__ Z, const bf16_t* __restrict__ KA, const bf16_t* __restrict__ VA, bf16_t* __restrict__ MIX, int S, int it) {
;     ...
;     for (int rho = 0; rho < 2; ++rho) {
;         __syncthreads();
;         attn_stage<200>(ka, va, Kt, Vt, (P0 >> 2) - 64, S >> 2, 2 * rho, 2, tid);
;         attn_stage<200>(ka, va, Kt + 200 * 72, Vt + 200 * 68, (P0 >> 2) - 64, S >> 2, 2 * rho + 1, 2, tid);
;         __syncthreads();
	v_mfma_f32_16x16x32_bf16 v[52:55], v[108:111], v[44:47], v[52:55]
	s_and_b64 vcc, vcc, s[36:37]
	v_subrev_u32_e32 v103, 28, v95
	v_cndmask_b32_e32 v35, v205, v35, vcc
	v_cmp_gt_u32_e32 vcc, s62, v103
	v_add_u32_e32 v103, 36, v96
	v_cmp_gt_u32_e64 s[36:37], s78, v103
	s_and_b64 vcc, vcc, s[36:37]
	v_subrev_u32_e32 v103, 27, v95
	v_cndmask_b32_e32 v52, v205, v52, vcc
	v_cmp_gt_u32_e32 vcc, s62, v103
	v_add_u32_e32 v103, 37, v96
	v_cmp_gt_u32_e64 s[36:37], s78, v103
	s_and_b64 vcc, vcc, s[36:37]
	v_subrev_u32_e32 v103, 26, v95
	v_cndmask_b32_e32 v53, v205, v53, vcc
	v_cmp_gt_u32_e32 vcc, s62, v103
	v_add_u32_e32 v103, 38, v96
	v_cmp_gt_u32_e64 s[36:37], s78, v103
	s_and_b64 vcc, vcc, s[36:37]
	v_subrev_u32_e32 v95, 25, v95
	v_cndmask_b32_e32 v54, v205, v54, vcc
	v_cmp_gt_u32_e32 vcc, s62, v95
	v_add_u32_e32 v95, 39, v96
	v_cmp_gt_u32_e64 s[36:37], s78, v95
	s_and_b64 vcc, vcc, s[36:37]
	v_cndmask_b32_e32 v55, v205, v55, vcc
	v_max_f32_e32 v95, v32, v33
	v_max_f32_e32 v96, v34, v35
	v_max_f32_e32 v103, v54, v55
	v_max3_f32 v103, v52, v53, v103
	v_max3_f32 v95, v95, v96, v103
	v_mov_b32_e32 v96, v95
	s_nop 1
	v_permlane16_swap_b32_e32 v95, v96
	v_max_f32_e32 v95, v95, v96
	v_mov_b32_e32 v96, v95
	s_nop 1
	v_permlane32_swap_b32_e32 v95, v96
	v_max3_f32 v183, v102, v95, v96
	v_sub_f32_e32 v32, v32, v183
	v_exp_f32_e32 v96, v32
	v_sub_f32_e32 v33, v33, v183
	v_sub_f32_e32 v95, v102, v183
	v_exp_f32_e32 v102, v33
	v_sub_f32_e32 v33, v34, v183
	v_exp_f32_e32 v103, v33
	v_sub_f32_e32 v33, v35, v183
	v_exp_f32_e32 v104, v33
	v_sub_f32_e32 v33, v52, v183
	v_add_f32_e32 v32, 0, v96
	v_exp_f32_e32 v105, v33
	v_sub_f32_e32 v33, v53, v183
	v_add_f32_e32 v32, v102, v32
	v_exp_f32_e32 v106, v33
	v_sub_f32_e32 v33, v54, v183
	v_add_f32_e32 v32, v103, v32
	v_exp_f32_e32 v107, v33
	v_sub_f32_e32 v33, v55, v183
	v_add_f32_e32 v32, v104, v32
	v_exp_f32_e32 v108, v33
	v_add_f32_e32 v32, v105, v32
	v_exp_f32_e32 v52, v95
	v_add_f32_e32 v32, v106, v32
	v_add_f32_e32 v32, v107, v32
	v_add_f32_e32 v184, v108, v32
	v_fmac_f32_e32 v184, v101, v52
	v_pk_mul_f32 v[34:35], v[38:39], v[52:53] op_sel_hi:[1,0]
	v_pk_mul_f32 v[32:33], v[36:37], v[52:53] op_sel_hi:[1,0]
	v_pk_mul_f32 v[38:39], v[50:51], v[52:53] op_sel_hi:[1,0]
	v_pk_mul_f32 v[36:37], v[48:49], v[52:53] op_sel_hi:[1,0]
	v_pk_mul_f32 v[50:51], v[30:31], v[52:53] op_sel_hi:[1,0]
	v_pk_mul_f32 v[48:49], v[28:29], v[52:53] op_sel_hi:[1,0]
	v_pk_mul_f32 v[54:55], v[26:27], v[52:53] op_sel_hi:[1,0]
	v_pk_mul_f32 v[52:53], v[24:25], v[52:53] op_sel_hi:[1,0]
	ds_read_b64_tr_b16 v[24:25], v112 offset:61952
	ds_read_b64_tr_b16 v[26:27], v112 offset:62496
	v_cvt_pk_bf16_f32 v102, v96, v102
	v_cvt_pk_bf16_f32 v103, v103, v104
	v_cvt_pk_bf16_f32 v104, v105, v106
	v_cvt_pk_bf16_f32 v105, v107, v108
	s_cmpk_eq_i32 s15, 0xc0
	s_waitcnt lgkmcnt(0)
	v_mfma_f32_16x16x32_bf16 v[28:31], v[24:27], v[102:105], v[32:35]
	ds_read_b64_tr_b16 v[24:25], v112 offset:61984
	ds_read_b64_tr_b16 v[26:27], v112 offset:62528
	s_nop 0
	ds_read_b64_tr_b16 v[32:33], v112 offset:62016
	ds_read_b64_tr_b16 v[34:35], v112 offset:62560
	s_waitcnt lgkmcnt(2)
	v_mfma_f32_16x16x32_bf16 v[24:27], v[24:27], v[102:105], v[36:39]
	s_nop 2
	ds_read_b64_tr_b16 v[36:37], v112 offset:62048
	ds_read_b64_tr_b16 v[38:39], v112 offset:62592
	s_waitcnt lgkmcnt(2)
	v_mfma_f32_16x16x32_bf16 v[32:35], v[32:35], v[102:105], v[48:51]
	s_waitcnt lgkmcnt(0)
	v_mfma_f32_16x16x32_bf16 v[36:39], v[36:39], v[102:105], v[52:55]
	s_cbranch_scc0 .LBB0_405
	v_or_b32_e32 v178, 2, v58
	v_lshlrev_b64 v[40:41], 7, v[178:179]
	v_or_b32_e32 v178, 2, v62
	v_lshlrev_b64 v[44:45], 7, v[178:179]
	v_or_b32_e32 v178, 2, v66
	v_lshlrev_b64 v[48:49], 7, v[178:179]
	v_or_b32_e32 v178, 2, v70
	v_lshl_add_u64 v[40:41], v[56:57], 0, v[40:41]
	v_lshlrev_b64 v[52:53], 7, v[178:179]
	v_or_b32_e32 v178, 2, v74
	s_barrier
	global_load_dwordx4 v[40:43], v[40:41], off
	v_lshl_add_u64 v[44:45], v[60:61], 0, v[44:45]
	v_lshlrev_b64 v[94:95], 7, v[178:179]
	global_load_dwordx4 v[44:47], v[44:45], off
	v_lshl_add_u64 v[48:49], v[64:65], 0, v[48:49]
	v_lshl_add_u64 v[94:95], v[72:73], 0, v[94:95]
	v_or_b32_e32 v178, 2, v78
	global_load_dwordx4 v[48:51], v[48:49], off
	v_lshl_add_u64 v[52:53], v[68:69], 0, v[52:53]
	global_load_dwordx4 v[102:105], v[94:95], off
	v_lshlrev_b64 v[94:95], 7, v[178:179]
	global_load_dwordx4 v[52:55], v[52:53], off
	v_lshl_add_u64 v[94:95], v[76:77], 0, v[94:95]
	v_or_b32_e32 v178, 2, v82
	global_load_dwordx4 v[106:109], v[94:95], off
	v_lshlrev_b64 v[94:95], 7, v[178:179]
	v_lshl_add_u64 v[94:95], v[80:81], 0, v[94:95]
	global_load_dwordx4 v[110:113], v[94:95], off
	v_or_b32_e32 v178, 3, v58
	s_mov_b32 s2, 0
	s_waitcnt vmcnt(6)
	ds_write2_b64 v85, v[40:41], v[42:43] offset1:1
	s_waitcnt vmcnt(5)
	ds_write2_b64 v87, v[44:45], v[46:47] offset1:1
	s_waitcnt vmcnt(4)
	ds_write2_b64 v89, v[48:49], v[50:51] offset1:1
	s_waitcnt vmcnt(2)
	ds_write2_b64 v90, v[52:53], v[54:55] offset1:1
	ds_write2_b64 v91, v[102:103], v[104:105] offset1:1
	s_waitcnt vmcnt(1)
	ds_write2_b64 v92, v[106:107], v[108:109] offset1:1
	s_waitcnt vmcnt(0)
	ds_write2_b64 v93, v[110:111], v[112:113] offset1:1
	v_lshlrev_b64 v[40:41], 7, v[178:179]
	v_or_b32_e32 v178, 3, v62
	v_lshlrev_b64 v[44:45], 7, v[178:179]
	v_or_b32_e32 v178, 3, v66
	v_lshlrev_b64 v[48:49], 7, v[178:179]
	v_or_b32_e32 v178, 3, v70
	v_lshl_add_u64 v[40:41], v[56:57], 0, v[40:41]
	v_lshlrev_b64 v[52:53], 7, v[178:179]
	v_or_b32_e32 v178, 3, v74
	global_load_dwordx4 v[40:43], v[40:41], off
	v_lshl_add_u64 v[44:45], v[60:61], 0, v[44:45]
	v_lshlrev_b64 v[56:57], 7, v[178:179]
	global_load_dwordx4 v[44:47], v[44:45], off
	v_lshl_add_u64 v[48:49], v[64:65], 0, v[48:49]
	v_lshl_add_u64 v[56:57], v[72:73], 0, v[56:57]
	v_or_b32_e32 v178, 3, v78
	global_load_dwordx4 v[48:51], v[48:49], off
	v_lshl_add_u64 v[52:53], v[68:69], 0, v[52:53]
	global_load_dwordx4 v[90:93], v[56:57], off
	v_lshlrev_b64 v[56:57], 7, v[178:179]
	global_load_dwordx4 v[52:55], v[52:53], off
	v_lshl_add_u64 v[56:57], v[76:77], 0, v[56:57]
	v_or_b32_e32 v178, 3, v82
	global_load_dwordx4 v[76:79], v[56:57], off
	v_lshlrev_b64 v[56:57], 7, v[178:179]
	v_lshl_add_u64 v[56:57], v[80:81], 0, v[56:57]
	global_load_dwordx4 v[80:83], v[56:57], off
	s_waitcnt vmcnt(6)
	ds_write2_b64 v97, v[40:41], v[42:43] offset1:1
	s_waitcnt vmcnt(5)
	ds_write2_b64 v98, v[44:45], v[46:47] offset1:1
	s_waitcnt vmcnt(4)
	ds_write2_b64 v99, v[48:49], v[50:51] offset1:1
	s_waitcnt vmcnt(2)
	ds_write2_b64 v100, v[52:53], v[54:55] offset1:1
	ds_write2_b64 v84, v[90:91], v[92:93] offset1:1
	s_waitcnt vmcnt(1)
	ds_write2_b64 v86, v[76:77], v[78:79] offset1:1
	s_waitcnt vmcnt(0)
	ds_write2_b64 v88, v[80:81], v[82:83] offset1:1
	s_waitcnt lgkmcnt(0)
	s_barrier
; __device__ __forceinline__ bf16x8 attn_softmax_step(const f32x4& sA, const f32x4& sB, int cb, int cq, int ncls, int g, float& m, float& lsum, f32x4 (&O)[4]) {
;     float s[8]; bool ok[8];
;     const int c0v = cb + 8 * g, d0 = c0v - cq + 64;
; #pragma unroll
;     for (int j = 0; j < 8; ++j) {
;         ok[j] = ((unsigned)(c0v + j) < (unsigned)ncls) && ((unsigned)(d0 + j) <= 128u);
;         s[j] = ok[j] ? (j < 4 ? sA[j] : sB[j - 4]) : -__builtin_inff(); }
;     float mx = fmaxf(fmaxf(fmaxf(s[0], s[1]), fmaxf(s[2], s[3])), fmaxf(fmaxf(s[4], s[5]), fmaxf(s[6], s[7])));
;     mx = xmax32(xmax16(mx));
;     const float mn = fmaxf(m, mx), alpha = __builtin_amdgcn_exp2f(m - mn);
;     m = mn;
;     float pj[8], ps_ = 0.f;
; #pragma unroll
;     for (int j = 0; j < 8; ++j) { pj[j] = __builtin_amdgcn_exp2f(s[j] - mn); ps_ += pj[j]; }
;     lsum = lsum * alpha + ps_;
; #pragma unroll
;     for (int nbk = 0; nbk < 4; ++nbk) O[nbk] *= alpha;
;     return pack8(pj);
; }
; __device__ __forceinline__ void attn_lds_step(const bf16_t* Kt, const bf16_t* Vt, int rowb, const bf16x8& q0, const bf16x8& q1, int cb, int cq, int ncls,
;                                               int qi, int g, float& m, float& lsum, f32x4 (&O)[4]) {
;     const bf16_t* kA = Kt + (rowb + 8 * (qi >> 2) + (qi & 3)) * 72 + 8 * g;
;     const bf16x8 ka0 = *(const bf16x8*)kA, ka1 = *(const bf16x8*)(kA + 32), kb0 = *(const bf16x8*)(kA + 4 * 72), kb1 = *(const bf16x8*)(kA + 4 * 72 + 32);
;     f32x4 sA = {0.f, 0.f, 0.f, 0.f}, sB = {0.f, 0.f, 0.f, 0.f};
;     sA = MFMA16(ka0, q0, sA); sA = MFMA16(ka1, q1, sA);
;     sB = MFMA16(kb0, q0, sB); sB = MFMA16(kb1, q1, sB);
;     const bf16x8 P = attn_softmax_step(sA, sB, cb, cq, ncls, g, m, lsum, O);
; #pragma unroll
;     for (int nbk = 0; nbk < 4; ++nbk) O[nbk] = MFMA16(gather8(Vt + (rowb + 8 * g) * 68 + 16 * nbk, 68, qi), P, O[nbk]);
; }
; __device__ __forceinline__ void attn_item(const bf16_t* __restrict__ Z, const bf16_t* __restrict__ KA, const bf16_t* __restrict__ VA, bf16_t* __restrict__ MIX, int S, int it) {
;     ...
;         const int r = rt[rho], cls = (r & 3) - 2 * rho, c0 = (P0 >> 2) + (r >> 2);
; #pragma unroll 2
;         for (int i2 = 0; i2 < 6; ++i2)
;             attn_lds_step(Kt + cls * 200 * 72, Vt + cls * 200 * 68, (r >> 2) + 32 * i2, q0[rho], q1[rho], c0 - 64 + 32 * i2, c0 + 4 * qi, S >> 2, qi, g, m[rho], lsum[rho], O[rho]);
.LBB0_407:
	v_add_u32_e32 v52, 0, v75
	ds_read_b128 v[40:43], v52
	ds_read_b128 v[44:47], v52 offset:64
	ds_read_b128 v[48:51], v52 offset:576
	ds_read_b128 v[52:55], v52 offset:640
	v_add_u32_e32 v75, 0x2400, v75
	s_waitcnt lgkmcnt(3)
	v_mfma_f32_16x16x32_bf16 v[40:43], v[40:43], v[0:3], 0
	s_waitcnt lgkmcnt(2)
	v_mfma_f32_16x16x32_bf16 v[40:43], v[44:47], v[4:7], v[40:43]
	s_waitcnt lgkmcnt(1)
	v_mfma_f32_16x16x32_bf16 v[44:47], v[48:51], v[0:3], 0
	v_add_u32_e32 v48, s2, v67
	v_subrev_u32_e32 v50, 64, v48
	v_add_u32_e32 v49, s2, v71
	v_cmp_gt_u32_e32 vcc, s62, v50
	v_cmp_gt_u32_e64 s[36:37], s78, v49
	s_and_b64 vcc, vcc, s[36:37]
	v_subrev_u32_e32 v50, 63, v48
	v_cndmask_b32_e32 v40, v205, v40, vcc
	v_cmp_gt_u32_e32 vcc, s62, v50
	v_add_u32_e32 v50, 1, v49
	v_cmp_gt_u32_e64 s[36:37], s78, v50
	s_and_b64 vcc, vcc, s[36:37]
	v_subrev_u32_e32 v50, 62, v48
	v_cndmask_b32_e32 v41, v205, v41, vcc
	v_cmp_gt_u32_e32 vcc, s62, v50
	v_add_u32_e32 v50, 2, v49
	v_cmp_gt_u32_e64 s[36:37], s78, v50
	s_and_b64 vcc, vcc, s[36:37]
	v_subrev_u32_e32 v50, 61, v48
	v_cndmask_b32_e32 v42, v205, v42, vcc
	v_cmp_gt_u32_e32 vcc, s62, v50
	v_add_u32_e32 v50, 3, v49
	v_cmp_gt_u32_e64 s[36:37], s78, v50
	s_waitcnt lgkmcnt(0)
	v_mfma_f32_16x16x32_bf16 v[44:47], v[52:55], v[4:7], v[44:47]
	s_and_b64 vcc, vcc, s[36:37]
	v_subrev_u32_e32 v50, 60, v48
	v_cndmask_b32_e32 v43, v205, v43, vcc
	v_cmp_gt_u32_e32 vcc, s62, v50
	v_add_u32_e32 v50, 4, v49
	v_cmp_gt_u32_e64 s[36:37], s78, v50
	s_and_b64 vcc, vcc, s[36:37]
	v_subrev_u32_e32 v50, 59, v48
	v_cndmask_b32_e32 v44, v205, v44, vcc
	v_cmp_gt_u32_e32 vcc, s62, v50
	v_add_u32_e32 v50, 5, v49
	v_cmp_gt_u32_e64 s[36:37], s78, v50
	s_and_b64 vcc, vcc, s[36:37]
	v_subrev_u32_e32 v50, 58, v48
	v_cndmask_b32_e32 v45, v205, v45, vcc
	v_cmp_gt_u32_e32 vcc, s62, v50
	v_add_u32_e32 v50, 6, v49
	v_cmp_gt_u32_e64 s[36:37], s78, v50
	s_and_b64 vcc, vcc, s[36:37]
	v_subrev_u32_e32 v50, 57, v48
	v_cndmask_b32_e32 v46, v205, v46, vcc
	v_cmp_gt_u32_e32 vcc, s62, v50
	v_add_u32_e32 v50, 7, v49
	v_cmp_gt_u32_e64 s[36:37], s78, v50
	s_and_b64 vcc, vcc, s[36:37]
	v_cndmask_b32_e32 v47, v205, v47, vcc
	v_max_f32_e32 v50, v40, v41
	v_max_f32_e32 v51, v42, v43
	v_max_f32_e32 v52, v46, v47
	v_max3_f32 v52, v44, v45, v52
	v_max3_f32 v50, v50, v51, v52
	v_mov_b32_e32 v51, v50
	s_nop 1
	v_permlane16_swap_b32_e32 v50, v51
	v_max_f32_e32 v50, v50, v51
	v_mov_b32_e32 v51, v50
	s_nop 1
	v_permlane32_swap_b32_e32 v50, v51
	v_max3_f32 v51, v177, v50, v51
	v_sub_f32_e32 v40, v40, v51
	v_exp_f32_e32 v53, v40
	v_sub_f32_e32 v41, v41, v51
	v_exp_f32_e32 v54, v41
	v_sub_f32_e32 v41, v42, v51
	v_exp_f32_e32 v55, v41
	v_sub_f32_e32 v41, v43, v51
	v_exp_f32_e32 v56, v41
	v_sub_f32_e32 v41, v44, v51
	v_add_f32_e32 v40, 0, v53
	v_exp_f32_e32 v57, v41
	v_sub_f32_e32 v41, v45, v51
	v_add_f32_e32 v40, v54, v40
	v_exp_f32_e32 v58, v41
	v_sub_f32_e32 v41, v46, v51
	v_sub_f32_e32 v52, v177, v51
	v_add_f32_e32 v40, v55, v40
	v_exp_f32_e32 v60, v41
	v_sub_f32_e32 v41, v47, v51
	v_add_f32_e32 v40, v56, v40
	v_exp_f32_e32 v61, v41
	v_exp_f32_e32 v52, v52
	v_add_f32_e32 v40, v57, v40
	v_add_f32_e32 v40, v58, v40
	v_add_f32_e32 v40, v60, v40
	v_add_f32_e32 v50, v61, v40
	v_pk_mul_f32 v[40:41], v[8:9], v[52:53] op_sel_hi:[1,0]
	v_pk_mul_f32 v[8:9], v[12:13], v[52:53] op_sel_hi:[1,0]
	v_cvt_pk_bf16_f32 v13, v55, v56
	v_add_u32_e32 v56, 0, v59
	v_fmac_f32_e32 v50, v185, v52
	v_pk_mul_f32 v[46:47], v[18:19], v[52:53] op_sel_hi:[1,0]
	v_pk_mul_f32 v[44:45], v[16:17], v[52:53] op_sel_hi:[1,0]
	v_pk_mul_f32 v[42:43], v[10:11], v[52:53] op_sel_hi:[1,0]
	v_pk_mul_f32 v[18:19], v[22:23], v[52:53] op_sel_hi:[1,0]
	v_pk_mul_f32 v[16:17], v[20:21], v[52:53] op_sel_hi:[1,0]
	v_pk_mul_f32 v[10:11], v[14:15], v[52:53] op_sel_hi:[1,0]
	v_cvt_pk_bf16_f32 v12, v53, v54
	ds_read_b64_tr_b16 v[22:23], v56 offset:58144
	ds_read_b64_tr_b16 v[20:21], v56 offset:57600
	ds_read_b64_tr_b16 v[52:53], v56 offset:57632
	v_cvt_pk_bf16_f32 v14, v57, v58
	v_cvt_pk_bf16_f32 v15, v60, v61
	ds_read_b64_tr_b16 v[54:55], v56 offset:58176
	v_add_u32_e32 v57, 0, v63
	s_waitcnt lgkmcnt(2)
	v_mfma_f32_16x16x32_bf16 v[20:23], v[20:23], v[12:15], v[44:47]
	s_nop 2
	ds_read_b64_tr_b16 v[44:45], v56 offset:57664
	ds_read_b64_tr_b16 v[46:47], v56 offset:58208
	s_add_i32 s2, s2, 64
	v_add_u32_e32 v59, 0x2200, v59
	s_waitcnt lgkmcnt(0)
	v_mfma_f32_16x16x32_bf16 v[16:19], v[44:47], v[12:15], v[16:19]
	ds_read_b64_tr_b16 v[44:45], v56 offset:57696
	ds_read_b64_tr_b16 v[46:47], v56 offset:58240
	v_add_u32_e32 v63, 0x2400, v63
	v_mfma_f32_16x16x32_bf16 v[40:43], v[52:55], v[12:15], v[40:43]
	s_waitcnt lgkmcnt(0)
	v_mfma_f32_16x16x32_bf16 v[8:11], v[44:47], v[12:15], v[8:11]
	ds_read_b128 v[12:15], v57
	ds_read_b128 v[44:47], v57 offset:64
	ds_read_b128 v[52:55], v57 offset:576
	ds_read_b128 v[76:79], v57 offset:640
	s_waitcnt lgkmcnt(3)
	v_mfma_f32_16x16x32_bf16 v[12:15], v[12:15], v[0:3], 0
	s_waitcnt lgkmcnt(2)
	v_mfma_f32_16x16x32_bf16 v[12:15], v[44:47], v[4:7], v[12:15]
	s_waitcnt lgkmcnt(1)
	v_mfma_f32_16x16x32_bf16 v[44:47], v[52:55], v[0:3], 0
	v_subrev_u32_e32 v52, 32, v48
	v_add_u32_e32 v53, 32, v49
	v_cmp_gt_u32_e32 vcc, s62, v52
	v_cmp_gt_u32_e64 s[36:37], s78, v53
	s_and_b64 vcc, vcc, s[36:37]
	v_subrev_u32_e32 v52, 31, v48
	v_cndmask_b32_e32 v12, v205, v12, vcc
	v_cmp_gt_u32_e32 vcc, s62, v52
	v_add_u32_e32 v52, 33, v49
	v_cmp_gt_u32_e64 s[36:37], s78, v52
	s_and_b64 vcc, vcc, s[36:37]
	v_subrev_u32_e32 v52, 30, v48
	v_cndmask_b32_e32 v13, v205, v13, vcc
	v_cmp_gt_u32_e32 vcc, s62, v52
	v_add_u32_e32 v52, 34, v49
	v_cmp_gt_u32_e64 s[36:37], s78, v52
	s_and_b64 vcc, vcc, s[36:37]
	v_subrev_u32_e32 v52, 29, v48
	v_cndmask_b32_e32 v14, v205, v14, vcc
	v_cmp_gt_u32_e32 vcc, s62, v52
	v_add_u32_e32 v52, 35, v49
	v_cmp_gt_u32_e64 s[36:37], s78, v52
	s_waitcnt lgkmcnt(0)
; __device__ __forceinline__ bf16x8 attn_softmax_step(const f32x4& sA, const f32x4& sB, int cb, int cq, int ncls, int g, float& m, float& lsum, f32x4 (&O)[4]) {
;     float s[8]; bool ok[8];
;     const int c0v = cb + 8 * g, d0 = c0v - cq + 64;
; #pragma unroll
;     for (int j = 0; j < 8; ++j) {
;         ok[j] = ((unsigned)(c0v + j) < (unsigned)ncls) && ((unsigned)(d0 + j) <= 128u);
;         s[j] = ok[j] ? (j < 4 ? sA[j] : sB[j - 4]) : -__builtin_inff(); }
;     float mx = fmaxf(fmaxf(fmaxf(s[0], s[1]), fmaxf(s[2], s[3])), fmaxf(fmaxf(s[4], s[5]), fmaxf(s[6], s[7])));
;     mx = xmax32(xmax16(mx));
;     const float mn = fmaxf(m, mx), alpha = __builtin_amdgcn_exp2f(m - mn);
;     m = mn;
;     float pj[8], ps_ = 0.f;
; #pragma unroll
;     for (int j = 0; j < 8; ++j) { pj[j] = __builtin_amdgcn_exp2f(s[j] - mn); ps_ += pj[j]; }
;     lsum = lsum * alpha + ps_;
; #pragma unroll
;     for (int nbk = 0; nbk < 4; ++nbk) O[nbk] *= alpha;
;     return pack8(pj);
; }
; __device__ __forceinline__ void attn_lds_step(const bf16_t* Kt, const bf16_t* Vt, int rowb, const bf16x8& q0, const bf16x8& q1, int cb, int cq, int ncls,
;                                               int qi, int g, float& m, float& lsum, f32x4 (&O)[4]) {
;     const bf16_t* kA = Kt + (rowb + 8 * (qi >> 2) + (qi & 3)) * 72 + 8 * g;
;     const bf16x8 ka0 = *(const bf16x8*)kA, ka1 = *(const bf16x8*)(kA + 32), kb0 = *(const bf16x8*)(kA + 4 * 72), kb1 = *(const bf16x8*)(kA + 4 * 72 + 32);
;     f32x4 sA = {0.f, 0.f, 0.f, 0.f}, sB = {0.f, 0.f, 0.f, 0.f};
;     sA = MFMA16(ka0, q0, sA); sA = MFMA16(ka1, q1, sA);
;     sB = MFMA16(kb0, q0, sB); sB = MFMA16(kb1, q1, sB);
;     const bf16x8 P = attn_softmax_step(sA, sB, cb, cq, ncls, g, m, lsum, O);
; #pragma unroll
;     for (int nbk = 0; nbk < 4; ++nbk) O[nbk] = MFMA16(gather8(Vt + (rowb + 8 * g) * 68 + 16 * nbk, 68, qi), P, O[nbk]);
; }
; __device__ __forceinline__ void attn_item(const bf16_t* __restrict__ Z, const bf16_t* __restrict__ KA, const bf16_t* __restrict__ VA, bf16_t* __restrict__ MIX, int S, int it) {
;     ...
; #pragma unroll
;     for (int ti = 0; ti < 2; ++ti) {
;         float l = lsum[ti]; l = xsum32(xsum16(l));
;         const float inv = 1.0f / l;
;         bf16_t* op = MIX + ((size_t)seq * S + P0 + rt[ti] + 16 * qi) * D + head * 64 + 4 * g;
; #pragma unroll
	v_mfma_f32_16x16x32_bf16 v[44:47], v[76:79], v[4:7], v[44:47]
	s_and_b64 vcc, vcc, s[36:37]
	v_subrev_u32_e32 v52, 28, v48
	v_cndmask_b32_e32 v15, v205, v15, vcc
	v_cmp_gt_u32_e32 vcc, s62, v52
	v_add_u32_e32 v52, 36, v49
	v_cmp_gt_u32_e64 s[36:37], s78, v52
	s_and_b64 vcc, vcc, s[36:37]
	v_subrev_u32_e32 v52, 27, v48
	v_cndmask_b32_e32 v44, v205, v44, vcc
	v_cmp_gt_u32_e32 vcc, s62, v52
	v_add_u32_e32 v52, 37, v49
	v_cmp_gt_u32_e64 s[36:37], s78, v52
	s_and_b64 vcc, vcc, s[36:37]
	v_subrev_u32_e32 v52, 26, v48
	v_cndmask_b32_e32 v45, v205, v45, vcc
	v_cmp_gt_u32_e32 vcc, s62, v52
	v_add_u32_e32 v52, 38, v49
	v_cmp_gt_u32_e64 s[36:37], s78, v52
	s_and_b64 vcc, vcc, s[36:37]
	v_subrev_u32_e32 v48, 25, v48
	v_cndmask_b32_e32 v46, v205, v46, vcc
	v_cmp_gt_u32_e32 vcc, s62, v48
	v_add_u32_e32 v48, 39, v49
	v_cmp_gt_u32_e64 s[36:37], s78, v48
	s_and_b64 vcc, vcc, s[36:37]
	v_cndmask_b32_e32 v47, v205, v47, vcc
	v_max_f32_e32 v48, v12, v13
	v_max_f32_e32 v49, v14, v15
	v_max_f32_e32 v52, v46, v47
	v_max3_f32 v52, v44, v45, v52
	v_max3_f32 v48, v48, v49, v52
	v_mov_b32_e32 v49, v48
	s_nop 1
	v_permlane16_swap_b32_e32 v48, v49
	v_max_f32_e32 v48, v48, v49
	v_mov_b32_e32 v49, v48
	s_nop 1
	v_permlane32_swap_b32_e32 v48, v49
	v_max3_f32 v177, v51, v48, v49
	v_sub_f32_e32 v12, v12, v177
	v_exp_f32_e32 v49, v12
	v_sub_f32_e32 v13, v13, v177
	v_sub_f32_e32 v48, v51, v177
	v_exp_f32_e32 v51, v13
	v_sub_f32_e32 v13, v14, v177
	v_exp_f32_e32 v52, v13
	v_sub_f32_e32 v13, v15, v177
	v_exp_f32_e32 v53, v13
	v_sub_f32_e32 v13, v44, v177
	v_add_f32_e32 v12, 0, v49
	v_exp_f32_e32 v54, v13
	v_sub_f32_e32 v13, v45, v177
	v_add_f32_e32 v12, v51, v12
	v_exp_f32_e32 v55, v13
	v_sub_f32_e32 v13, v46, v177
	v_add_f32_e32 v12, v52, v12
	v_exp_f32_e32 v57, v13
	v_sub_f32_e32 v13, v47, v177
	v_add_f32_e32 v12, v53, v12
	v_exp_f32_e32 v58, v13
	v_add_f32_e32 v12, v54, v12
	v_exp_f32_e32 v44, v48
	v_add_f32_e32 v12, v55, v12
	v_add_f32_e32 v12, v57, v12
	v_add_f32_e32 v185, v58, v12
	v_fmac_f32_e32 v185, v50, v44
	v_pk_mul_f32 v[14:15], v[22:23], v[44:45] op_sel_hi:[1,0]
	v_pk_mul_f32 v[12:13], v[20:21], v[44:45] op_sel_hi:[1,0]
	v_pk_mul_f32 v[22:23], v[42:43], v[44:45] op_sel_hi:[1,0]
	v_pk_mul_f32 v[20:21], v[40:41], v[44:45] op_sel_hi:[1,0]
	v_pk_mul_f32 v[42:43], v[18:19], v[44:45] op_sel_hi:[1,0]
	v_pk_mul_f32 v[40:41], v[16:17], v[44:45] op_sel_hi:[1,0]
	v_pk_mul_f32 v[46:47], v[10:11], v[44:45] op_sel_hi:[1,0]
	v_pk_mul_f32 v[44:45], v[8:9], v[44:45] op_sel_hi:[1,0]
	ds_read_b64_tr_b16 v[8:9], v56 offset:61952
	ds_read_b64_tr_b16 v[10:11], v56 offset:62496
	v_cvt_pk_bf16_f32 v48, v49, v51
	v_cvt_pk_bf16_f32 v49, v52, v53
	v_cvt_pk_bf16_f32 v50, v54, v55
	v_cvt_pk_bf16_f32 v51, v57, v58
	s_cmpk_eq_i32 s2, 0xc0
	s_waitcnt lgkmcnt(0)
	v_mfma_f32_16x16x32_bf16 v[16:19], v[8:11], v[48:51], v[12:15]
	ds_read_b64_tr_b16 v[8:9], v56 offset:61984
	ds_read_b64_tr_b16 v[10:11], v56 offset:62528
	s_nop 0
	ds_read_b64_tr_b16 v[12:13], v56 offset:62016
	ds_read_b64_tr_b16 v[14:15], v56 offset:62560
	s_waitcnt lgkmcnt(2)
	v_mfma_f32_16x16x32_bf16 v[8:11], v[8:11], v[48:51], v[20:23]
	s_waitcnt lgkmcnt(0)
	v_mfma_f32_16x16x32_bf16 v[20:23], v[12:15], v[48:51], v[40:43]
	ds_read_b64_tr_b16 v[12:13], v56 offset:62048
	ds_read_b64_tr_b16 v[14:15], v56 offset:62592
	s_waitcnt lgkmcnt(0)
	v_mfma_f32_16x16x32_bf16 v[12:15], v[12:15], v[48:51], v[44:47]
	s_cbranch_scc0 .LBB0_407
	v_mov_b32_e32 v2, v184
	s_nop 1
	v_permlane16_swap_b32_e32 v184, v2
	v_add_f32_e32 v2, v184, v2
	s_add_i32 s13, s13, s12
	s_lshl_b32 s2, s14, 1
	v_readlane_b32 s6, v254, 38
	v_mov_b32_e32 v3, v2
	v_readlane_b32 s7, v254, 39
	s_add_u32 s2, s6, s2
	v_permlane32_swap_b32_e32 v2, v3
	s_addc_u32 s3, s7, 0
	v_mov_b32_e32 v187, v179
	v_add_f32_e32 v2, v2, v3
	v_lshl_add_u64 v[0:1], s[2:3], 0, v[186:187]
	v_div_scale_f32 v3, s[2:3], v2, v2, 1.0
	v_rcp_f32_e32 v4, v3
	v_or_b32_e32 v178, s13, v181
	v_ashrrev_i32_e32 v183, 31, v182
	v_ashrrev_i32_e32 v181, 31, v180
	v_fma_f32 v5, -v3, v4, 1.0
	v_fmac_f32_e32 v4, v5, v4
	v_div_scale_f32 v5, vcc, 1.0, v2, 1.0
	v_mul_f32_e32 v6, v5, v4
	v_fma_f32 v7, -v3, v6, v5
	v_fmac_f32_e32 v6, v7, v4
	v_fma_f32 v3, -v3, v6, v5
	v_div_fmas_f32 v3, v3, v4, v6
	v_div_fixup_f32 v2, v3, v2, 1.0
	v_lshl_add_u64 v[4:5], v[178:179], 0, v[182:183]
	v_lshlrev_b64 v[4:5], 11, v[4:5]
	v_pk_mul_f32 v[6:7], v[28:29], v[2:3] op_sel_hi:[1,0]
	v_pk_mul_f32 v[28:29], v[30:31], v[2:3] op_sel_hi:[1,0]
	v_lshl_add_u64 v[4:5], v[0:1], 0, v[4:5]
	v_cvt_pk_bf16_f32 v6, v6, v7
	v_cvt_pk_bf16_f32 v7, v28, v29
	global_store_dwordx2 v[4:5], v[6:7], off
	v_pk_mul_f32 v[6:7], v[24:25], v[2:3] op_sel_hi:[1,0]
	v_pk_mul_f32 v[24:25], v[26:27], v[2:3] op_sel_hi:[1,0]
	v_cvt_pk_bf16_f32 v6, v6, v7
	v_cvt_pk_bf16_f32 v7, v24, v25
	global_store_dwordx2 v[4:5], v[6:7], off offset:32
	v_pk_mul_f32 v[6:7], v[32:33], v[2:3] op_sel_hi:[1,0]
	v_pk_mul_f32 v[24:25], v[34:35], v[2:3] op_sel_hi:[1,0]
	v_cvt_pk_bf16_f32 v6, v6, v7
	v_cvt_pk_bf16_f32 v7, v24, v25
	global_store_dwordx2 v[4:5], v[6:7], off offset:64
	v_pk_mul_f32 v[6:7], v[36:37], v[2:3] op_sel_hi:[1,0]
	v_pk_mul_f32 v[2:3], v[38:39], v[2:3] op_sel_hi:[1,0]
	v_cvt_pk_bf16_f32 v6, v6, v7
	v_cvt_pk_bf16_f32 v7, v2, v3
	v_mov_b32_e32 v2, v185
	s_nop 1
	v_permlane16_swap_b32_e32 v185, v2
	v_add_f32_e32 v2, v185, v2
	v_mov_b32_e32 v3, v2
	s_nop 1
	v_permlane32_swap_b32_e32 v2, v3
	v_add_f32_e32 v2, v2, v3
	v_div_scale_f32 v3, s[2:3], v2, v2, 1.0
	global_store_dwordx2 v[4:5], v[6:7], off offset:96
	v_rcp_f32_e32 v4, v3
	v_readlane_b32 s2, v254, 19
	s_add_i32 s5, s5, s2
	s_cmpk_gt_u32 s5, 0x7f
	v_fma_f32 v5, -v3, v4, 1.0
	v_fmac_f32_e32 v4, v5, v4
	v_div_scale_f32 v5, vcc, 1.0, v2, 1.0
	v_mul_f32_e32 v6, v5, v4
	v_fma_f32 v7, -v3, v6, v5
	v_fmac_f32_e32 v6, v7, v4
	v_fma_f32 v3, -v3, v6, v5
	v_div_fmas_f32 v3, v3, v4, v6
	v_lshl_add_u64 v[4:5], v[180:181], 0, v[178:179]
	v_div_fixup_f32 v2, v3, v2, 1.0
	v_lshlrev_b64 v[4:5], 11, v[4:5]
	v_lshl_add_u64 v[0:1], v[0:1], 0, v[4:5]
	v_pk_mul_f32 v[4:5], v[16:17], v[2:3] op_sel_hi:[1,0]
	v_pk_mul_f32 v[6:7], v[18:19], v[2:3] op_sel_hi:[1,0]
	v_cvt_pk_bf16_f32 v4, v4, v5
	v_cvt_pk_bf16_f32 v5, v6, v7
	global_store_dwordx2 v[0:1], v[4:5], off
	v_pk_mul_f32 v[4:5], v[8:9], v[2:3] op_sel_hi:[1,0]
	v_pk_mul_f32 v[6:7], v[10:11], v[2:3] op_sel_hi:[1,0]
	v_cvt_pk_bf16_f32 v4, v4, v5
	v_cvt_pk_bf16_f32 v5, v6, v7
	global_store_dwordx2 v[0:1], v[4:5], off offset:32
	v_pk_mul_f32 v[4:5], v[20:21], v[2:3] op_sel_hi:[1,0]
	v_pk_mul_f32 v[6:7], v[22:23], v[2:3] op_sel_hi:[1,0]
	v_cvt_pk_bf16_f32 v4, v4, v5
	v_cvt_pk_bf16_f32 v5, v6, v7
	global_store_dwordx2 v[0:1], v[4:5], off offset:64
	v_pk_mul_f32 v[4:5], v[12:13], v[2:3] op_sel_hi:[1,0]
	v_pk_mul_f32 v[2:3], v[14:15], v[2:3] op_sel_hi:[1,0]
	v_cvt_pk_bf16_f32 v4, v4, v5
	v_cvt_pk_bf16_f32 v5, v2, v3
	global_store_dwordx2 v[0:1], v[4:5], off offset:96
	s_barrier
	s_cbranch_scc0 .LBB0_400
